# attn64 loop: score-copy removed by register ping-pong; P2 tail cache-row conversion with 4 loads in flight; rstd loads hoisted in 4 GEMM epilogues
# speedup vs baseline: 1.0107x; 1.0107x over previous
.LBB0_492:
	s_add_i32 s15, s0, 0x18000
	s_cmp_gt_i32 s15, 0xffff
	s_cbranch_scc1 .Lcr2_cb
	s_cmpk_gt_i32 s15, 0x7fff
	s_cselect_b32 s4, 0xffff8000, 0
	s_cselect_b32 s6, s59, s57
	s_cselect_b32 s7, s58, s56
	s_cselect_b32 s8, s14, 0x31000000
	s_add_i32 s4, s4, s15
	s_ashr_i32 s5, s4, 31
	s_ashr_i32 s9, s4, 10
	s_and_b32 s16, s15, 0x3ff
	s_lshl_b64 s[4:5], s[4:5], 12
	s_add_u32 s4, s7, s4
	s_addc_u32 s5, s6, s5
	s_mul_i32 s6, s9, 0x440
	s_add_u32 s8, s88, s8
	s_addc_u32 s9, s89, 0
	s_add_i32 s6, s6, s16
	s_ashr_i32 s7, s6, 31
	s_lshl_b64 s[6:7], s[6:7], 11
	s_add_u32 s6, s8, s6
	s_addc_u32 s7, s9, s7
	s_mov_b32 s16, 0
	s_branch .Lcr2_go
.Lcr2_cb:
	s_cmp_gt_u32 s15, 0x17fff
	s_cbranch_scc1 .Lcr2_mem
	s_cmp_gt_u32 s15, 0x13fff
	s_cselect_b32 s4, 0xffffc000, 0
	s_cselect_b32 s17, s12, 0x22a00000
	s_cselect_b32 s18, s63, s61
	s_cselect_b32 s19, s62, s60
	s_cselect_b32 s20, s13, 0x39800000
	s_add_i32 s4, s4, s15
	s_add_i32 s4, s4, 0xffff0000
	s_ashr_i32 s21, s4, 9
	s_and_b32 s22, s15, 0x1ff
	s_and_b32 s8, s4, 0xfffffe00
	s_add_i32 s8, s8, s22
	s_sub_i32 s8, s8, 64
	s_ashr_i32 s9, s8, 31
	s_lshl_b64 s[8:9], s[8:9], 12
	s_add_u32 s6, s86, s17
	s_addc_u32 s7, s87, 0
	s_add_u32 s8, s6, s8
	s_addc_u32 s9, s7, s9
	s_ashr_i32 s5, s4, 31
	s_lshl_b64 s[4:5], s[4:5], 12
	s_add_u32 s4, s19, s4
	s_addc_u32 s5, s18, s5
	s_mul_i32 s6, s21, 0x240
	s_add_i32 s6, s6, s22
	s_ashr_i32 s7, s6, 31
	s_lshl_b64 s[6:7], s[6:7], 11
	s_add_u32 s16, s88, s20
	s_addc_u32 s17, s89, 0
	s_add_u32 s6, s16, s6
	s_addc_u32 s7, s17, s7
	s_cmp_gt_u32 s22, 63
	s_cselect_b32 s16, 1, 0
	s_branch .Lcr2_go
.Lcr2_mem:
	s_cmp_gt_u32 s15, 0x18fff
	s_cselect_b32 s6, 0xfffff000, 0
	s_cselect_b32 s16, s67, s65
	s_cselect_b32 s17, s66, s64
	s_cselect_b32 s18, s1, 0xa00000
	s_add_i32 s6, s6, s0
	s_ashr_i32 s7, s6, 31
	s_lshl_b64 s[4:5], s[6:7], 12
	s_add_u32 s4, s17, s4
	s_addc_u32 s5, s16, s5
	s_lshl_b64 s[6:7], s[6:7], 11
	s_add_u32 s8, s88, s18
	s_addc_u32 s9, s89, 0
	s_add_u32 s6, s8, s6
	s_addc_u32 s7, s9, s7
	s_mov_b32 s16, 0
.Lcr2_go:
	s_nop 0
	global_load_dwordx4 v[16:19], v6, s[4:5]
	global_load_dwordx4 v[20:23], v6, s[4:5] offset:1024
	global_load_dwordx4 v[24:27], v6, s[4:5] offset:2048
	global_load_dwordx4 v[28:31], v6, s[4:5] offset:3072
	s_waitcnt vmcnt(3)
	v_cvt_pk_bf16_f32 v2, v16, v17
	v_cvt_pk_bf16_f32 v3, v18, v19
	global_store_dwordx2 v8, v[2:3], s[6:7]
	s_waitcnt vmcnt(3)
	v_cvt_pk_bf16_f32 v4, v20, v21
	v_cvt_pk_bf16_f32 v5, v22, v23
	global_store_dwordx2 v8, v[4:5], s[6:7] offset:512
	s_waitcnt vmcnt(3)
	v_cvt_pk_bf16_f32 v10, v24, v25
	v_cvt_pk_bf16_f32 v11, v26, v27
	global_store_dwordx2 v8, v[10:11], s[6:7] offset:1024
	s_waitcnt vmcnt(3)
	v_cvt_pk_bf16_f32 v12, v28, v29
	v_cvt_pk_bf16_f32 v13, v30, v31
	global_store_dwordx2 v8, v[12:13], s[6:7] offset:1536
	s_cmp_eq_u32 s16, 0
	s_cbranch_scc1 .LBB0_491
	global_store_dwordx4 v6, v[16:19], s[8:9]
	global_store_dwordx4 v6, v[20:23], s[8:9] offset:1024
	global_store_dwordx4 v6, v[24:27], s[8:9] offset:2048
	global_store_dwordx4 v6, v[28:31], s[8:9] offset:3072
	s_branch .LBB0_491

.LBB0_643:
	s_lshl_b32 s7, s6, 8
	s_add_i32 s7, s7, s69
	v_add_u32_e32 v148, s7, v168
	v_ashrrev_i32_e32 v149, 31, v148
	v_lshl_add_u64 v[152:153], v[148:149], 2, s[20:21]
	global_load_dword v154, v[152:153], off
	global_load_dword v222, v[152:153], off offset:64
	global_load_dword v223, v[152:153], off offset:128
	global_load_dword v224, v[152:153], off offset:192
	global_load_dword v225, v[152:153], off offset:512
	global_load_dword v226, v[152:153], off offset:576
	global_load_dword v227, v[152:153], off offset:640
	global_load_dword v228, v[152:153], off offset:704
	s_lshl_b32 s7, s8, 8
	s_and_b32 s7, s7, 0x300
	s_or_b32 s7, s7, s70
	s_cmpk_gt_i32 s6, 0x7f
	s_cselect_b64 s[54:55], -1, 0
	s_cmp_lt_u32 s8, 4
	v_lshl_add_u32 v146, v146, 3, s7
	s_cselect_b64 s[6:7], -1, 0
	s_cmp_gt_u32 s8, 3
	s_cselect_b64 s[58:59], -1, 0
	s_cmp_eq_u32 s10, 3
	s_cselect_b64 s[8:9], -1, 0
	s_cmp_lg_u32 s10, 3
	s_cselect_b64 s[60:61], -1, 0
	s_cmp_lt_i32 s10, 4
	s_cselect_b64 s[56:57], -1, 0
	s_lshl_b32 s12, s13, 25
	s_cmp_eq_u32 s13, 0
	s_mov_b32 s10, 0x8680000
	s_cselect_b32 s14, s10, 0x8880000
	s_mov_b32 s10, 0x4400000
	s_cselect_b32 s11, s10, 0x6400000
	s_cmp_eq_u32 s13, 2
	s_mov_b32 s10, 0x8a80000
	s_mul_i32 s16, s13, 0x2200000
	s_mul_i32 s52, s13, 0x1200000
	s_cselect_b32 s13, s10, 0x9a80000
	s_mov_b32 s10, 0x8400000
	v_ashrrev_i32_e32 v147, 31, v146
	s_mov_b32 s53, s17
	s_cselect_b32 s10, s10, 0x8500000
	v_and_b32_e32 v167, 63, v168
	s_mov_b64 s[62:63], -1
	s_and_b64 vcc, exec, s[58:59]
	s_cbranch_vccz .LBB0_663
	s_and_b64 vcc, exec, s[60:61]
	s_cbranch_vccz .LBB0_660
	s_and_b64 vcc, exec, s[54:55]
	s_cbranch_vccz .LBB0_651
	v_add_u32_e32 v150, 0xffff8000, v148
	v_ashrrev_i32_e32 v155, 6, v150
	s_andn2_b64 vcc, exec, s[56:57]
	s_cbranch_vccnz .LBB0_648
	v_mul_lo_u32 v151, v155, s77
	v_or_b32_e32 v151, v151, v167
	s_lshl_b64 s[62:63], s[16:17], 1
	v_add_u32_e32 v156, 0x400, v151
	s_add_u32 s62, s51, s62
	v_ashrrev_i32_e32 v157, 31, v156
	s_addc_u32 s63, s66, s63
	v_lshlrev_b64 v[156:157], 11, v[156:157]
	s_lshl_b32 s15, s14, 2
	v_lshl_add_u64 v[156:157], s[62:63], 0, v[156:157]
	s_add_u32 s62, s0, s15
	v_ashrrev_i32_e32 v151, 31, v150
	s_addc_u32 s63, s1, 0
	v_lshlrev_b64 v[150:151], 12, v[150:151]
	v_lshl_add_u64 v[150:151], s[62:63], 0, v[150:151]
	v_lshl_add_u64 v[158:159], v[146:147], 1, v[156:157]
	v_lshl_add_u64 v[156:157], v[146:147], 2, v[150:151]
	s_mov_b64 s[62:63], 0

.LBB0_669:
	s_or_b64 exec, exec, s[6:7]
	s_nop 1
	v_mov_b32_e32 v114, v222
	v_add_u32_e32 v115, 16, v168
	v_and_b32_e32 v124, 63, v115
	v_cndmask_b32_e64 v115, 0, 1, s[58:59]
	v_add_u32_e32 v116, 16, v148
	v_cmp_ne_u32_e64 s[8:9], 1, v115
	v_cndmask_b32_e64 v115, 0, 1, s[60:61]
	v_ashrrev_i32_e32 v117, 31, v116
	s_mov_b64 s[62:63], -1
	s_andn2_b64 vcc, exec, s[58:59]
	v_cmp_ne_u32_e64 s[6:7], 1, v115
	s_cbranch_vccnz .LBB0_689
	s_and_b64 vcc, exec, s[6:7]
	s_mov_b64 s[58:59], -1
	s_cbranch_vccnz .LBB0_686
	s_andn2_b64 vcc, exec, s[54:55]
	s_cbranch_vccnz .LBB0_677
	v_add_u32_e32 v122, 0xffff8010, v148
	v_ashrrev_i32_e32 v115, 6, v122
	s_andn2_b64 vcc, exec, s[56:57]
	s_cbranch_vccnz .LBB0_674
	v_mul_lo_u32 v118, v115, s77
	v_or_b32_e32 v118, v118, v124
	s_lshl_b64 s[58:59], s[16:17], 1
	v_add_u32_e32 v118, 0x400, v118
	s_add_u32 s58, s51, s58
	v_ashrrev_i32_e32 v119, 31, v118
	s_addc_u32 s59, s66, s59
	v_lshlrev_b64 v[118:119], 11, v[118:119]
	s_lshl_b32 s15, s14, 2
	v_lshl_add_u64 v[118:119], s[58:59], 0, v[118:119]
	s_add_u32 s58, s0, s15
	v_ashrrev_i32_e32 v123, 31, v122
	v_lshl_add_u64 v[120:121], v[146:147], 1, v[118:119]
	s_addc_u32 s59, s1, 0
	v_lshlrev_b64 v[118:119], 12, v[122:123]
	v_lshl_add_u64 v[118:119], s[58:59], 0, v[118:119]
	v_lshl_add_u64 v[118:119], v[146:147], 2, v[118:119]
	s_mov_b64 s[58:59], 0

.LBB0_691:
	v_pk_mul_f32 v[110:111], v[110:111], v[114:115] op_sel_hi:[1,0]
	v_pk_mul_f32 v[106:107], v[106:107], v[114:115] op_sel_hi:[1,0]
	v_cmp_ne_u64_e32 vcc, 0, v[118:119]
	v_pk_mul_f32 v[112:113], v[112:113], v[114:115] op_sel_hi:[1,0]
	v_pk_mul_f32 v[108:109], v[108:109], v[114:115] op_sel_hi:[1,0]
	v_mov_b32_e32 v116, v150
	v_mov_b32_e32 v117, v150
	v_pk_mul_f32 v[126:127], v[150:151], v[110:111]
	v_pk_mul_f32 v[128:129], v[150:151], v[106:107]
	v_pk_mul_f32 v[122:123], v[116:117], v[112:113]
	v_pk_mul_f32 v[154:155], v[116:117], v[108:109]
	v_cvt_pk_bf16_f32 v126, v126, v127
	v_cvt_pk_bf16_f32 v127, v122, v123
	v_cvt_pk_bf16_f32 v128, v128, v129
	s_nop 0
	v_cvt_pk_bf16_f32 v129, v154, v155
	global_store_dwordx4 v[120:121], v[126:129], off
	s_and_saveexec_b64 s[58:59], vcc
	s_cbranch_execz .LBB0_693
	global_store_dwordx4 v[118:119], v[110:113], off
	global_store_dwordx4 v[118:119], v[106:109], off offset:16

.LBB0_695:
	s_or_b64 exec, exec, s[58:59]
	s_nop 1
	v_mov_b32_e32 v98, v223
	v_add_u32_e32 v100, 32, v148
	v_xor_b32_e32 v108, 32, v167
	v_ashrrev_i32_e32 v101, 31, v100
	s_and_b64 vcc, exec, s[8:9]
	s_mov_b64 s[58:59], -1
	s_cbranch_vccnz .LBB0_715
	s_and_b64 vcc, exec, s[6:7]
	s_cbranch_vccnz .LBB0_712
	s_andn2_b64 vcc, exec, s[54:55]
	s_cbranch_vccnz .LBB0_703
	v_add_u32_e32 v106, 0xffff8020, v148
	v_ashrrev_i32_e32 v99, 6, v106
	s_andn2_b64 vcc, exec, s[56:57]
	s_cbranch_vccnz .LBB0_700
	v_mul_lo_u32 v102, v99, s77
	v_or_b32_e32 v102, v102, v108
	s_lshl_b64 s[58:59], s[16:17], 1
	v_add_u32_e32 v102, 0x400, v102
	s_add_u32 s58, s51, s58
	v_ashrrev_i32_e32 v103, 31, v102
	s_addc_u32 s59, s66, s59
	v_lshlrev_b64 v[102:103], 11, v[102:103]
	s_lshl_b32 s15, s14, 2
	v_lshl_add_u64 v[102:103], s[58:59], 0, v[102:103]
	s_add_u32 s58, s0, s15
	v_ashrrev_i32_e32 v107, 31, v106
	v_lshl_add_u64 v[104:105], v[146:147], 1, v[102:103]
	s_addc_u32 s59, s1, 0
	v_lshlrev_b64 v[102:103], 12, v[106:107]
	v_lshl_add_u64 v[102:103], s[58:59], 0, v[102:103]
	v_lshl_add_u64 v[102:103], v[146:147], 2, v[102:103]
	s_mov_b64 s[58:59], 0

.LBB0_717:
	v_pk_mul_f32 v[94:95], v[94:95], v[98:99] op_sel_hi:[1,0]
	v_pk_mul_f32 v[90:91], v[90:91], v[98:99] op_sel_hi:[1,0]
	v_cmp_ne_u64_e32 vcc, 0, v[102:103]
	v_pk_mul_f32 v[96:97], v[96:97], v[98:99] op_sel_hi:[1,0]
	v_pk_mul_f32 v[92:93], v[92:93], v[98:99] op_sel_hi:[1,0]
	v_mov_b32_e32 v100, v150
	v_mov_b32_e32 v101, v150
	v_pk_mul_f32 v[110:111], v[150:151], v[94:95]
	v_pk_mul_f32 v[112:113], v[150:151], v[90:91]
	v_pk_mul_f32 v[106:107], v[100:101], v[96:97]
	v_pk_mul_f32 v[114:115], v[100:101], v[92:93]
	v_cvt_pk_bf16_f32 v110, v110, v111
	v_cvt_pk_bf16_f32 v111, v106, v107
	v_cvt_pk_bf16_f32 v112, v112, v113
	s_nop 0
	v_cvt_pk_bf16_f32 v113, v114, v115
	global_store_dwordx4 v[104:105], v[110:113], off
	s_and_saveexec_b64 s[58:59], vcc
	s_cbranch_execz .LBB0_719
	global_store_dwordx4 v[102:103], v[94:97], off
	global_store_dwordx4 v[102:103], v[90:93], off offset:16

.LBB0_721:
	s_or_b64 exec, exec, s[58:59]
	s_nop 1
	v_mov_b32_e32 v82, v224
	v_add_u32_e32 v83, 48, v168
	v_add_u32_e32 v84, 48, v148
	v_and_b32_e32 v92, 63, v83
	v_ashrrev_i32_e32 v85, 31, v84
	s_and_b64 vcc, exec, s[8:9]
	s_mov_b64 s[58:59], -1
	s_cbranch_vccnz .LBB0_741
	s_and_b64 vcc, exec, s[6:7]
	s_cbranch_vccnz .LBB0_738
	s_andn2_b64 vcc, exec, s[54:55]
	s_cbranch_vccnz .LBB0_729
	v_add_u32_e32 v90, 0xffff8030, v148
	v_ashrrev_i32_e32 v83, 6, v90
	s_andn2_b64 vcc, exec, s[56:57]
	s_cbranch_vccnz .LBB0_726
	v_mul_lo_u32 v86, v83, s77
	v_or_b32_e32 v86, v86, v92
	s_lshl_b64 s[58:59], s[16:17], 1
	v_add_u32_e32 v86, 0x400, v86
	s_add_u32 s58, s51, s58
	v_ashrrev_i32_e32 v87, 31, v86
	s_addc_u32 s59, s66, s59
	v_lshlrev_b64 v[86:87], 11, v[86:87]
	s_lshl_b32 s15, s14, 2
	v_lshl_add_u64 v[86:87], s[58:59], 0, v[86:87]
	s_add_u32 s58, s0, s15
	v_ashrrev_i32_e32 v91, 31, v90
	v_lshl_add_u64 v[88:89], v[146:147], 1, v[86:87]
	s_addc_u32 s59, s1, 0
	v_lshlrev_b64 v[86:87], 12, v[90:91]
	v_lshl_add_u64 v[86:87], s[58:59], 0, v[86:87]
	v_lshl_add_u64 v[86:87], v[146:147], 2, v[86:87]
	s_mov_b64 s[58:59], 0

.LBB0_743:
	v_pk_mul_f32 v[78:79], v[78:79], v[82:83] op_sel_hi:[1,0]
	v_pk_mul_f32 v[74:75], v[74:75], v[82:83] op_sel_hi:[1,0]
	v_cmp_ne_u64_e32 vcc, 0, v[86:87]
	v_pk_mul_f32 v[80:81], v[80:81], v[82:83] op_sel_hi:[1,0]
	v_pk_mul_f32 v[76:77], v[76:77], v[82:83] op_sel_hi:[1,0]
	v_mov_b32_e32 v84, v150
	v_mov_b32_e32 v85, v150
	v_pk_mul_f32 v[94:95], v[150:151], v[78:79]
	v_pk_mul_f32 v[96:97], v[150:151], v[74:75]
	v_pk_mul_f32 v[90:91], v[84:85], v[80:81]
	v_pk_mul_f32 v[98:99], v[84:85], v[76:77]
	v_cvt_pk_bf16_f32 v94, v94, v95
	v_cvt_pk_bf16_f32 v95, v90, v91
	v_cvt_pk_bf16_f32 v96, v96, v97
	s_nop 0
	v_cvt_pk_bf16_f32 v97, v98, v99
	global_store_dwordx4 v[88:89], v[94:97], off
	s_and_saveexec_b64 s[58:59], vcc
	s_cbranch_execz .LBB0_745
	global_store_dwordx4 v[86:87], v[78:81], off
	global_store_dwordx4 v[86:87], v[74:77], off offset:16

.LBB0_747:
	s_or_b64 exec, exec, s[58:59]
	s_nop 1
	v_mov_b32_e32 v66, v225
	v_add_u32_e32 v68, 0x80, v148
	v_ashrrev_i32_e32 v69, 31, v68
	s_and_b64 vcc, exec, s[8:9]
	s_mov_b64 s[58:59], -1
	s_cbranch_vccnz .LBB0_767
	s_and_b64 vcc, exec, s[6:7]
	s_cbranch_vccnz .LBB0_764
	s_andn2_b64 vcc, exec, s[54:55]
	s_cbranch_vccnz .LBB0_755
	v_add_u32_e32 v74, 0xffff8080, v148
	v_ashrrev_i32_e32 v67, 6, v74
	s_andn2_b64 vcc, exec, s[56:57]
	s_cbranch_vccnz .LBB0_752
	v_mul_lo_u32 v70, v67, s77
	v_or_b32_e32 v70, v70, v167
	s_lshl_b64 s[58:59], s[16:17], 1
	v_add_u32_e32 v70, 0x400, v70
	s_add_u32 s58, s51, s58
	v_ashrrev_i32_e32 v71, 31, v70
	s_addc_u32 s59, s66, s59
	v_lshlrev_b64 v[70:71], 11, v[70:71]
	s_lshl_b32 s15, s14, 2
	v_lshl_add_u64 v[70:71], s[58:59], 0, v[70:71]
	s_add_u32 s58, s0, s15
	v_ashrrev_i32_e32 v75, 31, v74
	v_lshl_add_u64 v[72:73], v[146:147], 1, v[70:71]
	s_addc_u32 s59, s1, 0
	v_lshlrev_b64 v[70:71], 12, v[74:75]
	v_lshl_add_u64 v[70:71], s[58:59], 0, v[70:71]
	v_lshl_add_u64 v[70:71], v[146:147], 2, v[70:71]
	s_mov_b64 s[58:59], 0

.LBB0_769:
	v_pk_mul_f32 v[64:65], v[64:65], v[66:67] op_sel_hi:[1,0]
	v_pk_mul_f32 v[62:63], v[62:63], v[66:67] op_sel_hi:[1,0]
	v_mov_b32_e32 v68, v150
	v_mov_b32_e32 v69, v150
	v_cmp_ne_u64_e32 vcc, 0, v[70:71]
	v_pk_mul_f32 v[60:61], v[60:61], v[66:67] op_sel_hi:[1,0]
	v_pk_mul_f32 v[58:59], v[58:59], v[66:67] op_sel_hi:[1,0]
	v_pk_mul_f32 v[76:77], v[68:69], v[64:65]
	v_pk_mul_f32 v[74:75], v[150:151], v[62:63]
	v_pk_mul_f32 v[78:79], v[68:69], v[60:61]
	v_pk_mul_f32 v[80:81], v[150:151], v[58:59]
	v_cvt_pk_bf16_f32 v74, v74, v75
	v_cvt_pk_bf16_f32 v75, v76, v77
	s_nop 0
	v_cvt_pk_bf16_f32 v76, v80, v81
	v_cvt_pk_bf16_f32 v77, v78, v79
	global_store_dwordx4 v[72:73], v[74:77], off
	s_and_saveexec_b64 s[58:59], vcc
	s_cbranch_execz .LBB0_771
	global_store_dwordx4 v[70:71], v[62:65], off
	global_store_dwordx4 v[70:71], v[58:61], off offset:16

.LBB0_773:
	s_or_b64 exec, exec, s[58:59]
	s_nop 1
	v_mov_b32_e32 v50, v226
	v_add_u32_e32 v52, 0x90, v148
	v_ashrrev_i32_e32 v53, 31, v52
	s_and_b64 vcc, exec, s[8:9]
	s_mov_b64 s[58:59], -1
	s_cbranch_vccnz .LBB0_793
	s_and_b64 vcc, exec, s[6:7]
	s_cbranch_vccnz .LBB0_790
	s_andn2_b64 vcc, exec, s[54:55]
	s_cbranch_vccnz .LBB0_781
	v_add_u32_e32 v58, 0xffff8090, v148
	v_ashrrev_i32_e32 v51, 6, v58
	s_andn2_b64 vcc, exec, s[56:57]
	s_cbranch_vccnz .LBB0_778
	v_mul_lo_u32 v54, v51, s77
	v_or_b32_e32 v54, v54, v124
	s_lshl_b64 s[58:59], s[16:17], 1
	v_add_u32_e32 v54, 0x400, v54
	s_add_u32 s58, s51, s58
	v_ashrrev_i32_e32 v55, 31, v54
	s_addc_u32 s59, s66, s59
	v_lshlrev_b64 v[54:55], 11, v[54:55]
	s_lshl_b32 s15, s14, 2
	v_lshl_add_u64 v[54:55], s[58:59], 0, v[54:55]
	s_add_u32 s58, s0, s15
	v_ashrrev_i32_e32 v59, 31, v58
	v_lshl_add_u64 v[56:57], v[146:147], 1, v[54:55]
	s_addc_u32 s59, s1, 0
	v_lshlrev_b64 v[54:55], 12, v[58:59]
	v_lshl_add_u64 v[54:55], s[58:59], 0, v[54:55]
	v_lshl_add_u64 v[54:55], v[146:147], 2, v[54:55]
	s_mov_b64 s[58:59], 0

.LBB0_795:
	v_pk_mul_f32 v[48:49], v[48:49], v[50:51] op_sel_hi:[1,0]
	v_pk_mul_f32 v[46:47], v[46:47], v[50:51] op_sel_hi:[1,0]
	v_mov_b32_e32 v52, v150
	v_mov_b32_e32 v53, v150
	v_cmp_ne_u64_e32 vcc, 0, v[54:55]
	v_pk_mul_f32 v[44:45], v[44:45], v[50:51] op_sel_hi:[1,0]
	v_pk_mul_f32 v[42:43], v[42:43], v[50:51] op_sel_hi:[1,0]
	v_pk_mul_f32 v[60:61], v[52:53], v[48:49]
	v_pk_mul_f32 v[58:59], v[150:151], v[46:47]
	v_pk_mul_f32 v[62:63], v[52:53], v[44:45]
	v_pk_mul_f32 v[64:65], v[150:151], v[42:43]
	v_cvt_pk_bf16_f32 v58, v58, v59
	v_cvt_pk_bf16_f32 v59, v60, v61
	s_nop 0
	v_cvt_pk_bf16_f32 v60, v64, v65
	v_cvt_pk_bf16_f32 v61, v62, v63
	global_store_dwordx4 v[56:57], v[58:61], off
	s_and_saveexec_b64 s[58:59], vcc
	s_cbranch_execz .LBB0_797
	global_store_dwordx4 v[54:55], v[46:49], off
	global_store_dwordx4 v[54:55], v[42:45], off offset:16

.LBB0_799:
	s_or_b64 exec, exec, s[58:59]
	s_nop 1
	v_mov_b32_e32 v34, v227
	v_add_u32_e32 v36, 0xa0, v148
	v_ashrrev_i32_e32 v37, 31, v36
	s_and_b64 vcc, exec, s[8:9]
	s_mov_b64 s[58:59], -1
	s_cbranch_vccnz .LBB0_819
	s_and_b64 vcc, exec, s[6:7]
	s_cbranch_vccnz .LBB0_816
	s_andn2_b64 vcc, exec, s[54:55]
	s_cbranch_vccnz .LBB0_807
	v_add_u32_e32 v42, 0xffff80a0, v148
	v_ashrrev_i32_e32 v35, 6, v42
	s_andn2_b64 vcc, exec, s[56:57]
	s_cbranch_vccnz .LBB0_804
	v_mul_lo_u32 v38, v35, s77
	v_or_b32_e32 v38, v38, v108
	s_lshl_b64 s[58:59], s[16:17], 1
	v_add_u32_e32 v38, 0x400, v38
	s_add_u32 s58, s51, s58
	v_ashrrev_i32_e32 v39, 31, v38
	s_addc_u32 s59, s66, s59
	v_lshlrev_b64 v[38:39], 11, v[38:39]
	s_lshl_b32 s15, s14, 2
	v_lshl_add_u64 v[38:39], s[58:59], 0, v[38:39]
	s_add_u32 s58, s0, s15
	v_ashrrev_i32_e32 v43, 31, v42
	v_lshl_add_u64 v[40:41], v[146:147], 1, v[38:39]
	s_addc_u32 s59, s1, 0
	v_lshlrev_b64 v[38:39], 12, v[42:43]
	v_lshl_add_u64 v[38:39], s[58:59], 0, v[38:39]
	v_lshl_add_u64 v[38:39], v[146:147], 2, v[38:39]
	s_mov_b64 s[58:59], 0

.LBB0_821:
	v_pk_mul_f32 v[32:33], v[32:33], v[34:35] op_sel_hi:[1,0]
	v_pk_mul_f32 v[30:31], v[30:31], v[34:35] op_sel_hi:[1,0]
	v_mov_b32_e32 v36, v150
	v_mov_b32_e32 v37, v150
	v_cmp_ne_u64_e32 vcc, 0, v[38:39]
	v_pk_mul_f32 v[28:29], v[28:29], v[34:35] op_sel_hi:[1,0]
	v_pk_mul_f32 v[26:27], v[26:27], v[34:35] op_sel_hi:[1,0]
	v_pk_mul_f32 v[44:45], v[36:37], v[32:33]
	v_pk_mul_f32 v[42:43], v[150:151], v[30:31]
	v_pk_mul_f32 v[46:47], v[36:37], v[28:29]
	v_pk_mul_f32 v[48:49], v[150:151], v[26:27]
	v_cvt_pk_bf16_f32 v42, v42, v43
	v_cvt_pk_bf16_f32 v43, v44, v45
	s_nop 0
	v_cvt_pk_bf16_f32 v44, v48, v49
	v_cvt_pk_bf16_f32 v45, v46, v47
	global_store_dwordx4 v[40:41], v[42:45], off
	s_and_saveexec_b64 s[58:59], vcc
	s_cbranch_execz .LBB0_823
	global_store_dwordx4 v[38:39], v[30:33], off
	global_store_dwordx4 v[38:39], v[26:29], off offset:16

.LBB0_825:
	s_or_b64 exec, exec, s[58:59]
	s_nop 1
	v_mov_b32_e32 v18, v228
	v_add_u32_e32 v20, 0xb0, v148
	v_ashrrev_i32_e32 v21, 31, v20
	s_and_b64 vcc, exec, s[8:9]
	s_mov_b64 s[8:9], -1
	s_cbranch_vccnz .LBB0_845
	s_and_b64 vcc, exec, s[6:7]
	s_mov_b64 s[6:7], -1
	s_cbranch_vccnz .LBB0_842
	v_cndmask_b32_e64 v19, 0, 1, s[56:57]
	s_andn2_b64 vcc, exec, s[54:55]
	v_cmp_ne_u32_e64 s[6:7], 1, v19
	s_cbranch_vccnz .LBB0_833
	v_add_u32_e32 v26, 0xffff80b0, v148
	v_ashrrev_i32_e32 v19, 6, v26
	s_and_b64 vcc, exec, s[6:7]
	s_cbranch_vccnz .LBB0_830
	v_mul_lo_u32 v22, v19, s77
	v_or_b32_e32 v22, v22, v92
	s_lshl_b64 s[8:9], s[16:17], 1
	v_add_u32_e32 v22, 0x400, v22
	s_add_u32 s8, s51, s8
	v_ashrrev_i32_e32 v23, 31, v22
	s_addc_u32 s9, s66, s9
	v_lshlrev_b64 v[22:23], 11, v[22:23]
	v_lshl_add_u64 v[22:23], s[8:9], 0, v[22:23]
	s_lshl_b32 s8, s14, 2
	s_add_u32 s8, s0, s8
	v_ashrrev_i32_e32 v27, 31, v26
	v_lshl_add_u64 v[24:25], v[146:147], 1, v[22:23]
	s_addc_u32 s9, s1, 0
	v_lshlrev_b64 v[22:23], 12, v[26:27]
	v_lshl_add_u64 v[22:23], s[8:9], 0, v[22:23]
	v_lshl_add_u64 v[22:23], v[146:147], 2, v[22:23]
	s_mov_b64 s[8:9], 0

.LBB0_847:
	v_pk_mul_f32 v[16:17], v[16:17], v[18:19] op_sel_hi:[1,0]
	v_pk_mul_f32 v[14:15], v[14:15], v[18:19] op_sel_hi:[1,0]
	v_mov_b32_e32 v20, v150
	v_mov_b32_e32 v21, v150
	v_cmp_ne_u64_e32 vcc, 0, v[22:23]
	v_pk_mul_f32 v[12:13], v[12:13], v[18:19] op_sel_hi:[1,0]
	v_pk_mul_f32 v[10:11], v[10:11], v[18:19] op_sel_hi:[1,0]
	v_pk_mul_f32 v[28:29], v[20:21], v[16:17]
	v_pk_mul_f32 v[26:27], v[150:151], v[14:15]
	v_pk_mul_f32 v[30:31], v[20:21], v[12:13]
	v_pk_mul_f32 v[32:33], v[150:151], v[10:11]
	v_cvt_pk_bf16_f32 v26, v26, v27
	v_cvt_pk_bf16_f32 v27, v28, v29
	s_nop 0
	v_cvt_pk_bf16_f32 v28, v32, v33
	v_cvt_pk_bf16_f32 v29, v30, v31
	global_store_dwordx4 v[24:25], v[26:29], off
	s_and_saveexec_b64 s[6:7], vcc
	s_cbranch_execz .LBB0_849
	global_store_dwordx4 v[22:23], v[14:17], off
	global_store_dwordx4 v[22:23], v[10:13], off offset:16

.LBB0_946:
	s_mul_hi_u32 s6, s81, 0xcccccccd
	s_lshr_b32 s6, s6, 2
	s_mul_i32 s6, s6, 0x14000
	v_subrev_u32_e32 v16, s6, v215
	s_cmp_lg_u32 0, -1
	s_cselect_b32 s6, 0, 0
	v_add_u32_e32 v16, s6, v16
	ds_read_b64_tr_b16 v[100:101], v16 offset:0
	ds_read_b64_tr_b16 v[102:103], v16 offset:0x800
	ds_read_b64_tr_b16 v[104:105], v16 offset:0x200
	ds_read_b64_tr_b16 v[106:107], v16 offset:0xa00
	ds_read_b64_tr_b16 v[108:109], v16 offset:0x400
	ds_read_b64_tr_b16 v[110:111], v16 offset:0xc00
	ds_read_b64_tr_b16 v[112:113], v16 offset:0x600
	ds_read_b64_tr_b16 v[114:115], v16 offset:0xe00
	ds_read_b64_tr_b16 v[116:117], v16 offset:0x1000
	ds_read_b64_tr_b16 v[118:119], v16 offset:0x1800
	ds_read_b64_tr_b16 v[120:121], v16 offset:0x1200
	ds_read_b64_tr_b16 v[122:123], v16 offset:0x1a00
	ds_read_b64_tr_b16 v[124:125], v16 offset:0x1400
	ds_read_b64_tr_b16 v[126:127], v16 offset:0x1c00
	ds_read_b64_tr_b16 v[128:129], v16 offset:0x1600
	ds_read_b64_tr_b16 v[130:131], v16 offset:0x1e00
	s_waitcnt lgkmcnt(8)
	s_nop 0
	v_mfma_f32_32x32x16_bf16 v[66:81], v[100:103], v[180:183], v[66:81]
	v_exp_f32_e32 v132, v132
	v_exp_f32_e32 v133, v133
	v_mfma_f32_32x32x16_bf16 v[50:65], v[104:107], v[180:183], v[50:65]
	v_exp_f32_e32 v134, v134
	v_exp_f32_e32 v135, v135
	v_mfma_f32_32x32x16_bf16 v[34:49], v[108:111], v[180:183], v[34:49]
	v_exp_f32_e32 v136, v136
	v_exp_f32_e32 v137, v137
	v_mfma_f32_32x32x16_bf16 v[18:33], v[112:115], v[180:183], v[18:33]
	v_exp_f32_e32 v138, v138
	v_exp_f32_e32 v139, v139
	ds_read_b64_tr_b16 v[100:101], v16 offset:0x2000
	ds_read_b64_tr_b16 v[102:103], v16 offset:0x2800
	ds_read_b64_tr_b16 v[104:105], v16 offset:0x2200
	ds_read_b64_tr_b16 v[106:107], v16 offset:0x2a00
	ds_read_b64_tr_b16 v[108:109], v16 offset:0x2400
	ds_read_b64_tr_b16 v[110:111], v16 offset:0x2c00
	ds_read_b64_tr_b16 v[112:113], v16 offset:0x2600
	ds_read_b64_tr_b16 v[114:115], v16 offset:0x2e00
	s_waitcnt lgkmcnt(8)
	v_mfma_f32_32x32x16_bf16 v[66:81], v[116:119], v[12:15], v[66:81]
	v_exp_f32_e32 v140, v140
	v_exp_f32_e32 v141, v141
	v_mfma_f32_32x32x16_bf16 v[50:65], v[120:123], v[12:15], v[50:65]
	v_exp_f32_e32 v142, v142
	v_exp_f32_e32 v143, v143
	v_mfma_f32_32x32x16_bf16 v[34:49], v[124:127], v[12:15], v[34:49]
	v_exp_f32_e32 v144, v144
	v_exp_f32_e32 v145, v145
	v_mfma_f32_32x32x16_bf16 v[18:33], v[128:131], v[12:15], v[18:33]
	v_exp_f32_e32 v146, v146
	v_exp_f32_e32 v147, v147
	ds_read_b64_tr_b16 v[12:13], v16 offset:0x3000
	ds_read_b64_tr_b16 v[14:15], v16 offset:0x3800
	ds_read_b64_tr_b16 v[116:117], v16 offset:0x3200
	ds_read_b64_tr_b16 v[118:119], v16 offset:0x3a00
	ds_read_b64_tr_b16 v[120:121], v16 offset:0x3400
	ds_read_b64_tr_b16 v[122:123], v16 offset:0x3c00
	ds_read_b64_tr_b16 v[124:125], v16 offset:0x3600
	ds_read_b64_tr_b16 v[126:127], v16 offset:0x3e00
	s_waitcnt lgkmcnt(8)
	v_mfma_f32_32x32x16_bf16 v[66:81], v[100:103], v[8:11], v[66:81]
	v_exp_f32_e32 v148, v148
	v_exp_f32_e32 v149, v149
	v_mfma_f32_32x32x16_bf16 v[50:65], v[104:107], v[8:11], v[50:65]
	v_exp_f32_e32 v150, v150
	v_exp_f32_e32 v151, v151
	v_mfma_f32_32x32x16_bf16 v[34:49], v[108:111], v[8:11], v[34:49]
	v_exp_f32_e32 v152, v152
	v_exp_f32_e32 v153, v153
	v_mfma_f32_32x32x16_bf16 v[18:33], v[112:115], v[8:11], v[18:33]
	v_exp_f32_e32 v154, v154
	v_exp_f32_e32 v155, v155
	s_waitcnt lgkmcnt(0)
	v_mfma_f32_32x32x16_bf16 v[66:81], v[12:15], v[4:7], v[66:81]
	v_exp_f32_e32 v156, v156
	v_exp_f32_e32 v157, v157
	v_mfma_f32_32x32x16_bf16 v[50:65], v[116:119], v[4:7], v[50:65]
	v_exp_f32_e32 v158, v158
	v_exp_f32_e32 v159, v159
	v_mfma_f32_32x32x16_bf16 v[34:49], v[120:123], v[4:7], v[34:49]
	v_exp_f32_e32 v160, v160
	v_exp_f32_e32 v161, v161
	v_mfma_f32_32x32x16_bf16 v[18:33], v[124:127], v[4:7], v[18:33]
	v_exp_f32_e32 v162, v162
	v_exp_f32_e32 v163, v163
	s_add_i32 s83, s84, 2
	s_cmp_ge_u32 s83, s50
	s_cselect_b64 s[68:69], -1, 0
	s_and_b64 vcc, exec, s[68:69]
	s_cbranch_vccnz .LBB0_948
	s_mul_hi_u32 s6, s13, 0xcccccccd
	s_lshr_b32 s6, s6, 2
	s_mul_i32 s6, s6, 0x14000
	s_sub_i32 s17, s14, s6
	s_min_i32 s6, s83, s49
	s_lshl_b64 s[18:19], s[6:7], 17
	s_add_u32 s20, s52, s18
	s_addc_u32 s21, s53, s19
	s_add_u32 s18, s66, s18
	s_addc_u32 s19, s67, s19
	s_cmp_lg_u32 0, -1
	s_cselect_b32 s6, 0, 0
	s_add_i32 s6, s17, s6
	s_add_i32 s17, s80, 0x4000
	s_and_b32 s17, s17, 0x6000
	s_add_i32 s17, s17, s11
	s_mov_b32 s22, m0
	s_mov_b32 m0, s6
	s_nop 0
	global_load_lds_dwordx4 v194, s[20:21]
	s_mov_b32 m0, s22
	s_add_u32 s20, s20, 0x10000
	s_addc_u32 s21, s21, 0
	s_addk_i32 s6, 0x2000
	s_mov_b32 s22, m0
	s_mov_b32 m0, s6
	s_nop 0
	global_load_lds_dwordx4 v194, s[20:21]
	s_mov_b32 m0, s22
	s_mov_b32 s6, m0
	s_mov_b32 m0, s17
	s_nop 0
	global_load_lds_dwordx4 v195, s[18:19]
	s_mov_b32 m0, s6
.LBB0_948:
	s_add_i32 s6, s10, 0x80
	s_cmpk_gt_i32 s6, 0xff41
	s_cselect_b64 s[70:71], -1, 0
	s_cmpk_lt_i32 s6, 0xff42
	s_cselect_b64 vcc, -1, 0
	v_cndmask_b32_e32 v4, 0, v192, vcc
	v_sub_f32_e32 v100, v4, v205
	v_cmp_neq_f32_e32 vcc, v100, v98
	s_cbranch_vccz .LBB0_950
	v_mov_b32_e32 v101, v100
	v_mov_b32_e32 v102, v100
	v_mov_b32_e32 v103, v100
	v_mov_b32_e32 v104, v100
	v_mov_b32_e32 v105, v100
	v_mov_b32_e32 v106, v100
	v_mov_b32_e32 v107, v100
	v_mov_b32_e32 v108, v100
	v_mov_b32_e32 v109, v100
	v_mov_b32_e32 v110, v100
	v_mov_b32_e32 v111, v100
	v_mov_b32_e32 v112, v100
	v_mov_b32_e32 v113, v100
	v_mov_b32_e32 v114, v100
	v_mov_b32_e32 v115, v100
	v_mov_b64_e32 v[82:83], v[100:101]
	v_mov_b64_e32 v[84:85], v[102:103]
	v_mov_b64_e32 v[86:87], v[104:105]
	v_mov_b64_e32 v[88:89], v[106:107]
	v_mov_b64_e32 v[90:91], v[108:109]
	v_mov_b64_e32 v[92:93], v[110:111]
	v_mov_b64_e32 v[94:95], v[112:113]
	v_mov_b64_e32 v[96:97], v[114:115]
	v_mov_b32_e32 v98, v100
.LBB0_950:
	v_add_f32_e32 v16, v3, v184
	s_and_b32 s17, s80, 0x6000
	s_add_i32 s17, s17, 0
	s_add_i32 s17, s17, 0x14000
	v_add_u32_e32 v3, s17, v206
	v_add_u32_e32 v8, s17, v210
	ds_read_b128 v[4:7], v3
	ds_read_b128 v[8:11], v8 offset:4096
	s_waitcnt lgkmcnt(1)
	v_mfma_f32_32x32x16_bf16 v[100:115], v[4:7], v[176:179], v[82:97]
	v_add_u32_e32 v3, s17, v207
	ds_read_b128 v[12:15], v3
	v_add_u32_e32 v3, s17, v211
	ds_read_b128 v[216:219], v3 offset:4096
	v_add_f32_e32 v3, 0, v132
	v_add_f32_e32 v3, v133, v3
	v_add_f32_e32 v3, v134, v3
	v_add_f32_e32 v3, v135, v3
	v_cvt_pk_bf16_f32 v180, v132, v133
	v_cvt_pk_bf16_f32 v181, v134, v135
	s_waitcnt lgkmcnt(2)
	v_mfma_f32_32x32x16_bf16 v[116:131], v[8:11], v[176:179], v[82:97]
	v_add_f32_e32 v3, v136, v3
	v_add_f32_e32 v3, v137, v3
	v_add_f32_e32 v3, v138, v3
	v_add_f32_e32 v3, v139, v3
	v_cvt_pk_bf16_f32 v182, v136, v137
	v_cvt_pk_bf16_f32 v183, v138, v139
	s_waitcnt lgkmcnt(1)
	v_mfma_f32_32x32x16_bf16 v[100:115], v[12:15], v[172:175], v[100:115]
	v_add_u32_e32 v4, s17, v208
	v_add_u32_e32 v8, s17, v212
	ds_read_b128 v[4:7], v4
	ds_read_b128 v[220:223], v8 offset:4096
	v_add_f32_e32 v3, v140, v3
	v_add_f32_e32 v3, v141, v3
	v_add_f32_e32 v3, v142, v3
	v_add_f32_e32 v3, v143, v3
	v_cvt_pk_bf16_f32 v12, v140, v141
	v_cvt_pk_bf16_f32 v13, v142, v143
	s_waitcnt lgkmcnt(2)
	v_mfma_f32_32x32x16_bf16 v[116:131], v[216:219], v[172:175], v[116:131]
	v_add_f32_e32 v3, v144, v3
	v_add_f32_e32 v3, v145, v3
	v_add_f32_e32 v3, v146, v3
	v_add_f32_e32 v3, v147, v3
	v_cvt_pk_bf16_f32 v14, v144, v145
	v_cvt_pk_bf16_f32 v15, v146, v147
	s_waitcnt lgkmcnt(1)
	v_mfma_f32_32x32x16_bf16 v[100:115], v[4:7], v[168:171], v[100:115]
	v_add_u32_e32 v8, s17, v209
	v_add_u32_e32 v9, s17, v213
	ds_read_b128 v[216:219], v8
	ds_read_b128 v[224:227], v9 offset:4096
	v_add_f32_e32 v3, v148, v3
	v_add_f32_e32 v3, v149, v3
	v_add_f32_e32 v3, v150, v3
	v_add_f32_e32 v3, v151, v3
	v_cvt_pk_bf16_f32 v8, v148, v149
	v_cvt_pk_bf16_f32 v9, v150, v151
	s_waitcnt lgkmcnt(2)
	v_mfma_f32_32x32x16_bf16 v[116:131], v[220:223], v[168:171], v[116:131]
	v_add_f32_e32 v3, v152, v3
	v_add_f32_e32 v3, v153, v3
	v_add_f32_e32 v3, v154, v3
	v_add_f32_e32 v3, v155, v3
	v_cvt_pk_bf16_f32 v10, v152, v153
	v_cvt_pk_bf16_f32 v11, v154, v155
	s_waitcnt lgkmcnt(1)
	v_mfma_f32_32x32x16_bf16 v[100:115], v[216:219], v[164:167], v[100:115]
	v_add_f32_e32 v3, v156, v3
	v_add_f32_e32 v3, v157, v3
	v_add_f32_e32 v3, v158, v3
	v_add_f32_e32 v3, v159, v3
	v_cvt_pk_bf16_f32 v4, v156, v157
	v_cvt_pk_bf16_f32 v5, v158, v159
	s_waitcnt lgkmcnt(0)
	v_mfma_f32_32x32x16_bf16 v[116:131], v[224:227], v[164:167], v[116:131]
	v_add_f32_e32 v3, v160, v3
	v_add_f32_e32 v3, v161, v3
	v_add_f32_e32 v3, v162, v3
	v_add_f32_e32 v17, v163, v3
	v_cvt_pk_bf16_f32 v6, v160, v161
	v_cvt_pk_bf16_f32 v7, v162, v163
	s_nop 0
	v_cmp_ge_f32_e32 vcc, s38, v17
	s_cmp_eq_u64 vcc, exec
	s_cbranch_scc0 .LBB0_960

.LBB0_953:
	s_andn2_b64 vcc, exec, s[70:71]
	s_cbranch_vccnz .LBB0_955
	v_add_u32_e32 v3, s10, v193
	v_add_u32_e32 v3, 0x180, v3
	s_nop 0
	v_add_u32_e32 v134, 1, v3
	v_med3_i32 v135, v134, 0, v204
	v_max_i32_e32 v134, 0xffffffe0, v134
	v_add_u32_e32 v134, 32, v134
	v_min_u32_e32 v134, 0x13f, v134
	v_lshl_add_u32 v136, v134, 2, s77
	v_add_u32_e32 v134, 2, v3
	v_med3_i32 v137, v134, 0, v204
	v_max_i32_e32 v134, 0xffffffe0, v134
	v_add_u32_e32 v134, 32, v134
	v_min_u32_e32 v134, 0x13f, v134
	v_lshl_add_u32 v138, v134, 2, s77
	v_add_u32_e32 v134, 3, v3
	v_max_i32_e32 v133, 0xffffffe0, v3
	v_med3_i32 v139, v134, 0, v204
	v_max_i32_e32 v134, 0xffffffe0, v134
	v_add_u32_e32 v133, 32, v133
	v_add_u32_e32 v134, 32, v134
	v_med3_i32 v132, v3, 0, v204
	v_min_u32_e32 v133, 0x13f, v133
	v_min_u32_e32 v134, 0x13f, v134
	v_lshl_add_u32 v132, v132, 2, s77
	v_lshl_add_u32 v133, v133, 2, s77
	v_lshl_add_u32 v135, v135, 2, s77
	v_lshl_add_u32 v137, v137, 2, s77
	v_lshl_add_u32 v139, v139, 2, s77
	v_lshl_add_u32 v140, v134, 2, s77
	ds_read_b32 v132, v132
	ds_read_b32 v134, v133
	ds_read_b32 v133, v135
	ds_read_b32 v135, v136
	ds_read_b32 v136, v137
	ds_read_b32 v138, v138
	ds_read_b32 v137, v139
	ds_read_b32 v139, v140
	v_add_u32_e32 v140, 8, v3
	v_med3_i32 v141, v140, 0, v204
	v_max_i32_e32 v140, 0xffffffe0, v140
	v_add_u32_e32 v140, 32, v140
	v_min_u32_e32 v140, 0x13f, v140
	v_lshl_add_u32 v142, v140, 2, s77
	v_add_u32_e32 v140, 9, v3
	v_med3_i32 v143, v140, 0, v204
	v_max_i32_e32 v140, 0xffffffe0, v140
	v_add_u32_e32 v140, 32, v140
	v_min_u32_e32 v140, 0x13f, v140
	v_lshl_add_u32 v144, v140, 2, s77
	v_add_u32_e32 v140, 10, v3
	v_med3_i32 v145, v140, 0, v204
	v_max_i32_e32 v140, 0xffffffe0, v140
	v_add_u32_e32 v140, 32, v140
	v_min_u32_e32 v140, 0x13f, v140
	v_lshl_add_u32 v146, v140, 2, s77
	v_add_u32_e32 v140, 11, v3
	v_med3_i32 v147, v140, 0, v204
	v_max_i32_e32 v140, 0xffffffe0, v140
	v_add_u32_e32 v140, 32, v140
	v_min_u32_e32 v140, 0x13f, v140
	v_lshl_add_u32 v141, v141, 2, s77
	v_lshl_add_u32 v143, v143, 2, s77
	v_lshl_add_u32 v145, v145, 2, s77
	v_lshl_add_u32 v147, v147, 2, s77
	v_lshl_add_u32 v148, v140, 2, s77
	ds_read_b32 v140, v141
	ds_read_b32 v142, v142
	ds_read_b32 v141, v143
	ds_read_b32 v143, v144
	ds_read_b32 v144, v145
	ds_read_b32 v146, v146
	ds_read_b32 v145, v147
	ds_read_b32 v147, v148
	v_add_u32_e32 v148, 16, v3
	v_med3_i32 v149, v148, 0, v204
	v_max_i32_e32 v148, 0xffffffe0, v148
	v_add_u32_e32 v148, 32, v148
	v_min_u32_e32 v148, 0x13f, v148
	v_lshl_add_u32 v150, v148, 2, s77
	v_add_u32_e32 v148, 17, v3
	v_med3_i32 v151, v148, 0, v204
	v_max_i32_e32 v148, 0xffffffe0, v148
	v_add_u32_e32 v148, 32, v148
	v_min_u32_e32 v148, 0x13f, v148
	v_lshl_add_u32 v152, v148, 2, s77
	v_add_u32_e32 v148, 18, v3
	v_med3_i32 v153, v148, 0, v204
	v_max_i32_e32 v148, 0xffffffe0, v148
	v_add_u32_e32 v148, 32, v148
	v_min_u32_e32 v148, 0x13f, v148
	v_lshl_add_u32 v154, v148, 2, s77
	v_add_u32_e32 v148, 19, v3
	v_med3_i32 v155, v148, 0, v204
	v_max_i32_e32 v148, 0xffffffe0, v148
	v_add_u32_e32 v148, 32, v148
	v_min_u32_e32 v148, 0x13f, v148
	v_lshl_add_u32 v149, v149, 2, s77
	v_lshl_add_u32 v151, v151, 2, s77
	v_lshl_add_u32 v153, v153, 2, s77
	v_lshl_add_u32 v155, v155, 2, s77
	v_lshl_add_u32 v156, v148, 2, s77
	ds_read_b32 v148, v149
	ds_read_b32 v150, v150
	ds_read_b32 v149, v151
	ds_read_b32 v151, v152
	ds_read_b32 v152, v153
	ds_read_b32 v154, v154
	ds_read_b32 v153, v155
	ds_read_b32 v155, v156
	v_add_u32_e32 v156, 24, v3
	v_add_u32_e32 v158, 25, v3
	v_add_u32_e32 v160, 26, v3
	v_add_u32_e32 v3, 27, v3
	v_med3_i32 v157, v156, 0, v204
	v_max_i32_e32 v156, 0xffffffe0, v156
	v_med3_i32 v159, v158, 0, v204
	v_max_i32_e32 v158, 0xffffffe0, v158
	v_med3_i32 v161, v160, 0, v204
	v_max_i32_e32 v160, 0xffffffe0, v160
	v_med3_i32 v162, v3, 0, v204
	v_max_i32_e32 v3, 0xffffffe0, v3
	v_add_u32_e32 v156, 32, v156
	v_add_u32_e32 v158, 32, v158
	v_add_u32_e32 v160, 32, v160
	v_add_u32_e32 v3, 32, v3
	v_lshl_add_u32 v157, v157, 2, s77
	v_min_u32_e32 v156, 0x13f, v156
	v_min_u32_e32 v158, 0x13f, v158
	v_min_u32_e32 v160, 0x13f, v160
	v_min_u32_e32 v3, 0x13f, v3
	v_lshl_add_u32 v156, v156, 2, s77
	v_lshl_add_u32 v159, v159, 2, s77
	v_lshl_add_u32 v158, v158, 2, s77
	v_lshl_add_u32 v161, v161, 2, s77
	v_lshl_add_u32 v160, v160, 2, s77
	v_lshl_add_u32 v162, v162, 2, s77
	s_waitcnt lgkmcnt(14)
	v_pk_add_f32 v[102:103], v[102:103], v[136:137]
	v_pk_add_f32 v[100:101], v[100:101], v[132:133]
	s_waitcnt lgkmcnt(9)
	v_pk_add_f32 v[106:107], v[106:107], v[144:145]
	v_pk_add_f32 v[104:105], v[104:105], v[140:141]
	v_lshl_add_u32 v3, v3, 2, s77
	ds_read_b32 v132, v157
	ds_read_b32 v136, v156
	ds_read_b32 v140, v161
	ds_read_b32 v141, v162
	ds_read_b32 v133, v159
	ds_read_b32 v145, v3
	ds_read_b32 v144, v160
	ds_read_b32 v137, v158
	s_waitcnt lgkmcnt(9)
	v_pk_add_f32 v[110:111], v[110:111], v[152:153]
	v_pk_add_f32 v[108:109], v[108:109], v[148:149]
	s_waitcnt lgkmcnt(4)
	v_pk_add_f32 v[114:115], v[114:115], v[140:141]
	s_waitcnt lgkmcnt(3)
	v_pk_add_f32 v[112:113], v[112:113], v[132:133]
	v_pk_add_f32 v[118:119], v[118:119], v[138:139]
	v_pk_add_f32 v[116:117], v[116:117], v[134:135]
	v_pk_add_f32 v[122:123], v[122:123], v[146:147]
	v_pk_add_f32 v[120:121], v[120:121], v[142:143]
	v_pk_add_f32 v[126:127], v[126:127], v[154:155]
	v_pk_add_f32 v[124:125], v[124:125], v[150:151]
	s_waitcnt lgkmcnt(1)
	v_pk_add_f32 v[130:131], v[130:131], v[144:145]
	s_waitcnt lgkmcnt(0)
	v_pk_add_f32 v[128:129], v[128:129], v[136:137]
.LBB0_955:
.LBB0_956:
	s_mul_hi_u32 s10, s92, 0xcccccccd
	s_lshr_b32 s10, s10, 2
	v_pk_add_f32 v[184:185], v[16:17], v[16:17] op_sel:[1,0] op_sel_hi:[0,1]
	s_mul_i32 s10, s10, 0x14000
	v_subrev_u32_e32 v3, s10, v214
	s_cmp_lg_u32 0, -1
	s_cselect_b32 s10, 0, 0
	v_add_u32_e32 v3, s10, v3
	ds_read_b64_tr_b16 v[132:133], v3 offset:0
	ds_read_b64_tr_b16 v[134:135], v3 offset:0x800
	ds_read_b64_tr_b16 v[136:137], v3 offset:0x200
	ds_read_b64_tr_b16 v[138:139], v3 offset:0xa00
	ds_read_b64_tr_b16 v[140:141], v3 offset:0x400
	ds_read_b64_tr_b16 v[142:143], v3 offset:0xc00
	ds_read_b64_tr_b16 v[144:145], v3 offset:0x600
	ds_read_b64_tr_b16 v[146:147], v3 offset:0xe00
	ds_read_b64_tr_b16 v[148:149], v3 offset:0x1000
	ds_read_b64_tr_b16 v[150:151], v3 offset:0x1800
	ds_read_b64_tr_b16 v[152:153], v3 offset:0x1200
	ds_read_b64_tr_b16 v[154:155], v3 offset:0x1a00
	ds_read_b64_tr_b16 v[156:157], v3 offset:0x1400
	ds_read_b64_tr_b16 v[158:159], v3 offset:0x1c00
	ds_read_b64_tr_b16 v[160:161], v3 offset:0x1600
	ds_read_b64_tr_b16 v[162:163], v3 offset:0x1e00
	s_waitcnt lgkmcnt(8)
	s_nop 0
	v_mfma_f32_32x32x16_bf16 v[66:81], v[132:135], v[180:183], v[66:81]
	v_exp_f32_e32 v100, v100
	v_exp_f32_e32 v101, v101
	v_mfma_f32_32x32x16_bf16 v[50:65], v[136:139], v[180:183], v[50:65]
	v_exp_f32_e32 v102, v102
	v_exp_f32_e32 v103, v103
	v_mfma_f32_32x32x16_bf16 v[34:49], v[140:143], v[180:183], v[34:49]
	v_exp_f32_e32 v104, v104
	v_exp_f32_e32 v105, v105
	v_mfma_f32_32x32x16_bf16 v[18:33], v[144:147], v[180:183], v[18:33]
	v_exp_f32_e32 v106, v106
	v_exp_f32_e32 v107, v107
	ds_read_b64_tr_b16 v[132:133], v3 offset:0x2000
	ds_read_b64_tr_b16 v[134:135], v3 offset:0x2800
	ds_read_b64_tr_b16 v[136:137], v3 offset:0x2200
	ds_read_b64_tr_b16 v[138:139], v3 offset:0x2a00
	ds_read_b64_tr_b16 v[140:141], v3 offset:0x2400
	ds_read_b64_tr_b16 v[142:143], v3 offset:0x2c00
	ds_read_b64_tr_b16 v[144:145], v3 offset:0x2600
	ds_read_b64_tr_b16 v[146:147], v3 offset:0x2e00
	s_waitcnt lgkmcnt(8)
	v_mfma_f32_32x32x16_bf16 v[66:81], v[148:151], v[12:15], v[66:81]
	v_exp_f32_e32 v108, v108
	v_exp_f32_e32 v109, v109
	v_mfma_f32_32x32x16_bf16 v[50:65], v[152:155], v[12:15], v[50:65]
	v_exp_f32_e32 v110, v110
	v_exp_f32_e32 v111, v111
	v_mfma_f32_32x32x16_bf16 v[34:49], v[156:159], v[12:15], v[34:49]
	v_exp_f32_e32 v112, v112
	v_exp_f32_e32 v113, v113
	v_mfma_f32_32x32x16_bf16 v[18:33], v[160:163], v[12:15], v[18:33]
	v_exp_f32_e32 v114, v114
	v_exp_f32_e32 v115, v115
	ds_read_b64_tr_b16 v[12:13], v3 offset:0x3000
	ds_read_b64_tr_b16 v[14:15], v3 offset:0x3800
	ds_read_b64_tr_b16 v[148:149], v3 offset:0x3200
	ds_read_b64_tr_b16 v[150:151], v3 offset:0x3a00
	ds_read_b64_tr_b16 v[152:153], v3 offset:0x3400
	ds_read_b64_tr_b16 v[154:155], v3 offset:0x3c00
	ds_read_b64_tr_b16 v[156:157], v3 offset:0x3600
	ds_read_b64_tr_b16 v[158:159], v3 offset:0x3e00
	s_waitcnt lgkmcnt(8)
	v_mfma_f32_32x32x16_bf16 v[66:81], v[132:135], v[8:11], v[66:81]
	v_exp_f32_e32 v116, v116
	v_exp_f32_e32 v117, v117
	v_mfma_f32_32x32x16_bf16 v[50:65], v[136:139], v[8:11], v[50:65]
	v_exp_f32_e32 v118, v118
	v_exp_f32_e32 v119, v119
	v_mfma_f32_32x32x16_bf16 v[34:49], v[140:143], v[8:11], v[34:49]
	v_exp_f32_e32 v120, v120
	v_exp_f32_e32 v121, v121
	v_mfma_f32_32x32x16_bf16 v[18:33], v[144:147], v[8:11], v[18:33]
	v_exp_f32_e32 v122, v122
	v_exp_f32_e32 v123, v123
	s_waitcnt lgkmcnt(0)
	v_mfma_f32_32x32x16_bf16 v[66:81], v[12:15], v[4:7], v[66:81]
	v_exp_f32_e32 v124, v124
	v_exp_f32_e32 v125, v125
	v_mfma_f32_32x32x16_bf16 v[50:65], v[148:151], v[4:7], v[50:65]
	v_exp_f32_e32 v126, v126
	v_exp_f32_e32 v127, v127
	v_mfma_f32_32x32x16_bf16 v[34:49], v[152:155], v[4:7], v[34:49]
	v_exp_f32_e32 v128, v128
	v_exp_f32_e32 v129, v129
	v_mfma_f32_32x32x16_bf16 v[18:33], v[156:159], v[4:7], v[18:33]
	v_exp_f32_e32 v130, v130
	v_exp_f32_e32 v131, v131
	s_waitcnt vmcnt(0) lgkmcnt(0)
	s_barrier
	s_addk_i32 s80, 0x4000
	v_add_u32_e32 v214, 0x8000, v214
	s_add_i32 s92, s92, 2
	s_add_i32 s14, s14, 0x8000
	s_add_i32 s13, s13, 2
	v_add_u32_e32 v215, 0x8000, v215
	s_add_i32 s81, s81, 2
	s_add_i32 s15, s15, 0x8000
	s_add_i32 s12, s12, 2
	s_and_b64 vcc, exec, s[68:69]
	s_cbranch_vccnz .LBB0_962
	s_mov_b32 s10, s6
	s_mov_b32 s84, s83
	s_add_i32 s6, s84, 1
	s_cmp_ge_u32 s6, s50
	s_cbranch_scc0 .LBB0_937
	s_branch .LBB0_938

.LBB0_959:
	s_mov_b32 s30, s16
	s_mov_b32 s31, s16
	s_mov_b32 s17, s16
	s_mov_b32 s18, s16
	s_mov_b32 s19, s16
	s_mov_b32 s20, s16
	s_mov_b32 s21, s16
	s_mov_b32 s22, s16
	s_mov_b32 s23, s16
	s_mov_b32 s24, s16
	s_mov_b32 s25, s16
	s_mov_b32 s26, s16
	s_mov_b32 s27, s16
	s_mov_b32 s28, s16
	s_mov_b32 s29, s16
	v_mov_b64_e32 v[146:147], s[30:31]
	v_mov_b64_e32 v[144:145], s[28:29]
	v_mov_b64_e32 v[142:143], s[26:27]
	v_mov_b64_e32 v[140:141], s[24:25]
	v_mov_b64_e32 v[138:139], s[22:23]
	v_mov_b64_e32 v[136:137], s[20:21]
	v_mov_b64_e32 v[134:135], s[18:19]
	v_mov_b64_e32 v[132:133], s[16:17]
	v_mov_b64_e32 v[162:163], v[146:147]
	v_mov_b64_e32 v[160:161], v[144:145]
	v_mov_b64_e32 v[158:159], v[142:143]
	v_mov_b64_e32 v[156:157], v[140:141]
	v_mov_b64_e32 v[154:155], v[138:139]
	v_mov_b64_e32 v[152:153], v[136:137]
	v_mov_b64_e32 v[150:151], v[134:135]
	v_mov_b64_e32 v[148:149], v[132:133]
	s_cbranch_execz .LBB0_943
	s_branch .LBB0_946
.LBB0_960:
	v_mov_b32_e32 v3, v17
	v_mov_b32_e32 v4, v17
	s_nop 1
	v_permlane32_swap_b32_e32 v3, v4
	v_add_f32_e32 v3, v3, v4
	v_rcp_f32_e32 v4, v3
	v_cmp_lt_f32_e32 vcc, s38, v3
	v_log_f32_e32 v3, v3
	s_nop 0
	v_cndmask_b32_e32 v12, 1.0, v4, vcc
	v_pk_mul_f32 v[6:7], v[160:161], v[12:13] op_sel_hi:[1,0]
	v_cndmask_b32_e32 v3, 0, v3, vcc
	v_pk_mul_f32 v[4:5], v[156:157], v[12:13] op_sel_hi:[1,0]
	v_pk_mul_f32 v[10:11], v[152:153], v[12:13] op_sel_hi:[1,0]
	v_pk_mul_f32 v[8:9], v[148:149], v[12:13] op_sel_hi:[1,0]
	v_pk_mul_f32 v[80:81], v[80:81], v[12:13] op_sel_hi:[1,0]
	v_pk_mul_f32 v[78:79], v[78:79], v[12:13] op_sel_hi:[1,0]
	v_pk_mul_f32 v[76:77], v[76:77], v[12:13] op_sel_hi:[1,0]
	v_pk_mul_f32 v[74:75], v[74:75], v[12:13] op_sel_hi:[1,0]
	v_pk_mul_f32 v[72:73], v[72:73], v[12:13] op_sel_hi:[1,0]
	v_pk_mul_f32 v[70:71], v[70:71], v[12:13] op_sel_hi:[1,0]
	v_pk_mul_f32 v[68:69], v[68:69], v[12:13] op_sel_hi:[1,0]
	v_pk_mul_f32 v[66:67], v[66:67], v[12:13] op_sel_hi:[1,0]
	v_pk_mul_f32 v[64:65], v[64:65], v[12:13] op_sel_hi:[1,0]
	v_pk_mul_f32 v[62:63], v[62:63], v[12:13] op_sel_hi:[1,0]
	v_pk_mul_f32 v[60:61], v[60:61], v[12:13] op_sel_hi:[1,0]
	v_pk_mul_f32 v[58:59], v[58:59], v[12:13] op_sel_hi:[1,0]
	v_pk_mul_f32 v[56:57], v[56:57], v[12:13] op_sel_hi:[1,0]
	v_pk_mul_f32 v[54:55], v[54:55], v[12:13] op_sel_hi:[1,0]
	v_pk_mul_f32 v[52:53], v[52:53], v[12:13] op_sel_hi:[1,0]
	v_pk_mul_f32 v[50:51], v[50:51], v[12:13] op_sel_hi:[1,0]
	v_pk_mul_f32 v[48:49], v[48:49], v[12:13] op_sel_hi:[1,0]
	v_pk_mul_f32 v[46:47], v[46:47], v[12:13] op_sel_hi:[1,0]
	v_pk_mul_f32 v[44:45], v[44:45], v[12:13] op_sel_hi:[1,0]
	v_pk_mul_f32 v[42:43], v[42:43], v[12:13] op_sel_hi:[1,0]
	v_pk_mul_f32 v[40:41], v[40:41], v[12:13] op_sel_hi:[1,0]
	v_pk_mul_f32 v[38:39], v[38:39], v[12:13] op_sel_hi:[1,0]
	v_pk_mul_f32 v[36:37], v[36:37], v[12:13] op_sel_hi:[1,0]
	v_pk_mul_f32 v[34:35], v[34:35], v[12:13] op_sel_hi:[1,0]
	v_pk_mul_f32 v[32:33], v[32:33], v[12:13] op_sel_hi:[1,0]
	v_pk_mul_f32 v[30:31], v[30:31], v[12:13] op_sel_hi:[1,0]
	v_pk_mul_f32 v[28:29], v[28:29], v[12:13] op_sel_hi:[1,0]
	v_pk_mul_f32 v[26:27], v[26:27], v[12:13] op_sel_hi:[1,0]
	v_pk_mul_f32 v[24:25], v[24:25], v[12:13] op_sel_hi:[1,0]
	v_pk_mul_f32 v[22:23], v[22:23], v[12:13] op_sel_hi:[1,0]
	v_pk_mul_f32 v[20:21], v[20:21], v[12:13] op_sel_hi:[1,0]
	v_pk_mul_f32 v[18:19], v[18:19], v[12:13] op_sel_hi:[1,0]
	v_pk_mul_f32 v[14:15], v[144:145], v[12:13] op_sel_hi:[1,0]
	v_pk_mul_f32 v[16:17], v[16:17], v[12:13] op_sel_hi:[1,0]
	v_add_f32_e32 v205, v205, v3
	v_sub_f32_e32 v115, v115, v3
	v_sub_f32_e32 v114, v114, v3
	v_sub_f32_e32 v113, v113, v3
	v_sub_f32_e32 v112, v112, v3
	v_sub_f32_e32 v111, v111, v3
	v_sub_f32_e32 v110, v110, v3
	v_sub_f32_e32 v109, v109, v3
	v_sub_f32_e32 v108, v108, v3
	v_sub_f32_e32 v107, v107, v3
	v_sub_f32_e32 v106, v106, v3
	v_sub_f32_e32 v105, v105, v3
	v_sub_f32_e32 v104, v104, v3
	v_sub_f32_e32 v103, v103, v3
	v_sub_f32_e32 v102, v102, v3
	v_sub_f32_e32 v101, v101, v3
	v_sub_f32_e32 v100, v100, v3
	v_sub_f32_e32 v131, v131, v3
	v_sub_f32_e32 v130, v130, v3
	v_sub_f32_e32 v129, v129, v3
	v_sub_f32_e32 v128, v128, v3
	v_sub_f32_e32 v127, v127, v3
	v_sub_f32_e32 v126, v126, v3
	v_sub_f32_e32 v125, v125, v3
	v_sub_f32_e32 v124, v124, v3
	v_sub_f32_e32 v123, v123, v3
	v_sub_f32_e32 v122, v122, v3
	v_sub_f32_e32 v121, v121, v3
	v_sub_f32_e32 v120, v120, v3
	v_sub_f32_e32 v119, v119, v3
	v_sub_f32_e32 v118, v118, v3
	v_sub_f32_e32 v117, v117, v3
	v_sub_f32_e32 v116, v116, v3
	v_pk_mul_f32 v[162:163], v[162:163], v[12:13] op_sel_hi:[1,0]
	v_pk_mul_f32 v[158:159], v[158:159], v[12:13] op_sel_hi:[1,0]
	v_pk_mul_f32 v[154:155], v[154:155], v[12:13] op_sel_hi:[1,0]
	v_pk_mul_f32 v[150:151], v[150:151], v[12:13] op_sel_hi:[1,0]
	v_pk_mul_f32 v[146:147], v[146:147], v[12:13] op_sel_hi:[1,0]
	v_pk_mul_f32 v[142:143], v[142:143], v[12:13] op_sel_hi:[1,0]
	v_pk_mul_f32 v[140:141], v[140:141], v[12:13] op_sel_hi:[1,0]
	v_pk_mul_f32 v[138:139], v[138:139], v[12:13] op_sel_hi:[1,0]
	v_pk_mul_f32 v[136:137], v[136:137], v[12:13] op_sel_hi:[1,0]
	v_pk_mul_f32 v[134:135], v[134:135], v[12:13] op_sel_hi:[1,0]
	v_pk_mul_f32 v[132:133], v[132:133], v[12:13] op_sel_hi:[1,0]
	s_nop 0
	v_cvt_pk_bf16_f32 v180, v132, v133
	v_cvt_pk_bf16_f32 v181, v134, v135
	v_cvt_pk_bf16_f32 v182, v136, v137
	v_cvt_pk_bf16_f32 v183, v138, v139
	v_cvt_pk_bf16_f32 v12, v140, v141
	v_cvt_pk_bf16_f32 v13, v142, v143
	v_cvt_pk_bf16_f32 v14, v14, v15
	v_cvt_pk_bf16_f32 v15, v146, v147
	v_cvt_pk_bf16_f32 v8, v8, v9
	v_cvt_pk_bf16_f32 v9, v150, v151
	v_cvt_pk_bf16_f32 v10, v10, v11
	v_cvt_pk_bf16_f32 v11, v154, v155
	v_cvt_pk_bf16_f32 v4, v4, v5
	v_cvt_pk_bf16_f32 v5, v158, v159
	v_cvt_pk_bf16_f32 v6, v6, v7
	v_cvt_pk_bf16_f32 v7, v162, v163
	s_branch .LBB0_951

.LBB0_1133:
	s_lshl_b32 s53, s59, 7
	v_mov_b32_e32 v86, v164
	v_mov_b32_e32 v90, v1
	s_or_b32 s53, s53, s38
	s_lshl_b32 s45, s58, 8
	v_lshl_add_u32 v170, v86, 3, s53
	s_add_i32 s45, s45, s35
	v_ashrrev_i32_e32 v171, 31, v170
	v_lshlrev_b64 v[86:87], 2, v[170:171]
	v_add_u32_e32 v172, s45, v90
	v_lshl_add_u64 v[88:89], s[6:7], 0, v[86:87]
	v_ashrrev_i32_e32 v173, 31, v172
	v_lshl_add_u64 v[86:87], s[26:27], 0, v[86:87]
	global_load_dwordx4 v[98:101], v[88:89], off
	v_lshl_add_u64 v[162:163], v[172:173], 2, s[16:17]
	global_load_dword v174, v[162:163], off
	global_load_dword v222, v[162:163], off offset:64
	global_load_dword v223, v[162:163], off offset:128
	global_load_dword v224, v[162:163], off offset:192
	global_load_dword v225, v[162:163], off offset:512
	global_load_dword v226, v[162:163], off offset:576
	global_load_dword v227, v[162:163], off offset:640
	global_load_dword v228, v[162:163], off offset:704
	global_load_dwordx4 v[106:109], v[86:87], off
	global_load_dwordx4 v[90:93], v[88:89], off offset:16
	s_nop 0
	global_load_dwordx4 v[86:89], v[86:87], off offset:16
	s_mov_b64 s[58:59], 0x10000
	s_andn2_b64 vcc, exec, s[4:5]
	s_mov_b64 s[4:5], -1
	s_waitcnt vmcnt(0)
	v_fma_f32 v138, v138, v174, v106
	v_fma_f32 v142, v142, v174, v98
	v_fma_f32 v135, v135, v174, v91
	v_med3_f32 v142, v142, s51, v169
	v_med3_f32 v135, v135, s51, v169
	v_fma_f32 v134, v134, v174, v90
	v_mul_f32_e32 v142, 0xbfb8aa3b, v142
	v_mul_f32_e32 v135, 0xbfb8aa3b, v135
	v_med3_f32 v134, v134, s51, v169
	v_exp_f32_e32 v142, v142
	v_exp_f32_e32 v135, v135
	v_fma_f32 v131, v131, v174, v87
	v_mul_f32_e32 v134, 0xbfb8aa3b, v134
	v_med3_f32 v138, v138, s51, v169
	v_med3_f32 v131, v131, s51, v169
	v_exp_f32_e32 v134, v134
	v_fma_f32 v130, v130, v174, v86
	v_mul_f32_e32 v138, 0xbfb8aa3b, v138
	v_mul_f32_e32 v131, 0xbfb8aa3b, v131
	v_med3_f32 v130, v130, s51, v169
	v_exp_f32_e32 v138, v138
	v_exp_f32_e32 v131, v131
	v_add_f32_e32 v142, 1.0, v142
	v_add_f32_e32 v135, 1.0, v135
	v_mul_f32_e32 v130, 0xbfb8aa3b, v130
	v_rcp_f32_e32 v142, v142
	v_rcp_f32_e32 v135, v135
	v_exp_f32_e32 v130, v130
	v_add_f32_e32 v134, 1.0, v134
	v_rcp_f32_e32 v134, v134
	v_add_f32_e32 v138, 1.0, v138
	v_add_f32_e32 v131, 1.0, v131
	v_fma_f32 v143, v143, v174, v99
	v_fma_f32 v144, v144, v174, v100
	v_fma_f32 v136, v136, v174, v92
	v_rcp_f32_e32 v175, v138
	v_mul_f32_e32 v138, v138, v142
	v_rcp_f32_e32 v142, v131
	v_mul_f32_e32 v131, v131, v135
	v_fma_f32 v135, v137, v174, v93
	v_fma_f32 v145, v145, v174, v101
	v_med3_f32 v143, v143, s51, v169
	v_med3_f32 v144, v144, s51, v169
	v_med3_f32 v136, v136, s51, v169
	v_add_f32_e32 v130, 1.0, v130
	v_med3_f32 v135, v135, s51, v169
	v_med3_f32 v145, v145, s51, v169
	v_mul_f32_e32 v143, 0xbfb8aa3b, v143
	v_mul_f32_e32 v144, 0xbfb8aa3b, v144
	v_rcp_f32_e32 v179, v130
	v_mul_f32_e32 v130, v130, v134
	v_mul_f32_e32 v134, 0xbfb8aa3b, v136
	v_mul_f32_e32 v135, 0xbfb8aa3b, v135
	v_mul_f32_e32 v145, 0xbfb8aa3b, v145
	v_exp_f32_e32 v143, v143
	v_exp_f32_e32 v144, v144
	v_exp_f32_e32 v134, v134
	v_exp_f32_e32 v135, v135
	v_fma_f32 v139, v139, v174, v107
	v_fma_f32 v140, v140, v174, v108
	v_fma_f32 v132, v132, v174, v88
	v_exp_f32_e32 v145, v145
	v_fma_f32 v133, v133, v174, v89
	v_fma_f32 v141, v141, v174, v109
	v_med3_f32 v139, v139, s51, v169
	v_med3_f32 v140, v140, s51, v169
	v_med3_f32 v132, v132, s51, v169
	v_med3_f32 v133, v133, s51, v169
	v_med3_f32 v141, v141, s51, v169
	v_mul_f32_e32 v139, 0xbfb8aa3b, v139
	v_mul_f32_e32 v140, 0xbfb8aa3b, v140
	v_mul_f32_e32 v132, 0xbfb8aa3b, v132
	v_mul_f32_e32 v133, 0xbfb8aa3b, v133
	v_mul_f32_e32 v141, 0xbfb8aa3b, v141
	v_exp_f32_e32 v139, v139
	v_exp_f32_e32 v140, v140
	v_add_f32_e32 v143, 1.0, v143
	v_add_f32_e32 v144, 1.0, v144
	v_exp_f32_e32 v132, v132
	v_add_f32_e32 v134, 1.0, v134
	v_exp_f32_e32 v133, v133
	v_add_f32_e32 v135, 1.0, v135
	v_exp_f32_e32 v141, v141
	v_add_f32_e32 v145, 1.0, v145
	v_rcp_f32_e32 v143, v143
	v_rcp_f32_e32 v144, v144
	v_rcp_f32_e32 v134, v134
	v_rcp_f32_e32 v135, v135
	v_rcp_f32_e32 v145, v145
	v_add_f32_e32 v139, 1.0, v139
	v_add_f32_e32 v140, 1.0, v140
	v_add_f32_e32 v132, 1.0, v132
	v_add_f32_e32 v133, 1.0, v133
	v_add_f32_e32 v141, 1.0, v141
	v_rcp_f32_e32 v176, v139
	v_rcp_f32_e32 v177, v140
	v_mul_f32_e32 v139, v139, v143
	v_mul_f32_e32 v140, v140, v144
	v_rcp_f32_e32 v143, v132
	v_mul_f32_e32 v132, v132, v134
	v_rcp_f32_e32 v144, v133
	v_mul_f32_e32 v133, v133, v135
	v_rcp_f32_e32 v178, v141
	v_mul_f32_e32 v141, v141, v145
	v_cvt_pk_bf16_f32 v134, v138, v139
	v_cvt_pk_bf16_f32 v135, v140, v141
	v_cvt_pk_bf16_f32 v136, v130, v131
	v_cvt_pk_bf16_f32 v137, v132, v133
	v_lshlrev_b64 v[132:133], 12, v[172:173]
	v_lshl_add_u64 v[138:139], s[18:19], 0, v[132:133]
	v_lshlrev_b64 v[130:131], 1, v[170:171]
	v_lshl_add_u64 v[138:139], v[138:139], 0, v[130:131]
	global_store_dwordx4 v[138:139], v[134:137], off
	v_lshl_add_u64 v[138:139], s[20:21], 0, v[132:133]
	v_lshl_add_u64 v[138:139], v[138:139], 0, v[130:131]
	v_cvt_pk_bf16_f32 v134, v175, v176
	v_cvt_pk_bf16_f32 v135, v177, v178
	v_cvt_pk_bf16_f32 v136, v179, v142
	v_cvt_pk_bf16_f32 v137, v143, v144
	global_store_dwordx4 v[138:139], v[134:137], off
	s_nop 1
	v_mov_b32_e32 v136, v222
	v_fma_f32 v127, v127, v136, v99
	v_fma_f32 v118, v118, v136, v90
	v_med3_f32 v127, v127, s51, v169
	v_med3_f32 v118, v118, s51, v169
	v_mul_f32_e32 v127, 0xbfb8aa3b, v127
	v_mul_f32_e32 v118, 0xbfb8aa3b, v118
	v_exp_f32_e32 v127, v127
	v_exp_f32_e32 v118, v118
	v_fma_f32 v123, v123, v136, v107
	v_fma_f32 v114, v114, v136, v86
	v_fma_f32 v128, v128, v136, v100
	v_med3_f32 v123, v123, s51, v169
	v_med3_f32 v114, v114, s51, v169
	v_fma_f32 v119, v119, v136, v91
	v_med3_f32 v128, v128, s51, v169
	v_mul_f32_e32 v123, 0xbfb8aa3b, v123
	v_mul_f32_e32 v114, 0xbfb8aa3b, v114
	v_med3_f32 v119, v119, s51, v169
	v_mul_f32_e32 v128, 0xbfb8aa3b, v128
	v_exp_f32_e32 v123, v123
	v_add_f32_e32 v127, 1.0, v127
	v_exp_f32_e32 v114, v114
	v_add_f32_e32 v118, 1.0, v118
	v_mul_f32_e32 v119, 0xbfb8aa3b, v119
	v_exp_f32_e32 v128, v128
	v_rcp_f32_e32 v127, v127
	v_rcp_f32_e32 v118, v118
	v_exp_f32_e32 v119, v119
	v_fma_f32 v124, v124, v136, v108
	v_fma_f32 v115, v115, v136, v87
	v_med3_f32 v124, v124, s51, v169
	v_med3_f32 v115, v115, s51, v169
	v_fma_f32 v116, v116, v136, v88
	v_mul_f32_e32 v124, 0xbfb8aa3b, v124
	v_add_f32_e32 v123, 1.0, v123
	v_add_f32_e32 v114, 1.0, v114
	v_mul_f32_e32 v115, 0xbfb8aa3b, v115
	v_med3_f32 v116, v116, s51, v169
	v_exp_f32_e32 v124, v124
	v_add_f32_e32 v128, 1.0, v128
	v_rcp_f32_e32 v138, v123
	v_mul_f32_e32 v123, v123, v127
	v_exp_f32_e32 v115, v115
	v_rcp_f32_e32 v127, v114
	v_mul_f32_e32 v118, v114, v118
	v_add_f32_e32 v114, 1.0, v119
	v_mul_f32_e32 v116, 0xbfb8aa3b, v116
	v_rcp_f32_e32 v128, v128
	v_rcp_f32_e32 v114, v114
	v_exp_f32_e32 v116, v116
	v_add_f32_e32 v124, 1.0, v124
	v_add_f32_e32 v115, 1.0, v115
	v_fma_f32 v119, v120, v136, v92
	v_rcp_f32_e32 v139, v124
	v_mul_f32_e32 v124, v124, v128
	v_med3_f32 v119, v119, s51, v169
	v_rcp_f32_e32 v120, v115
	v_mul_f32_e32 v128, v115, v114
	v_add_f32_e32 v115, 1.0, v116
	v_fma_f32 v116, v121, v136, v93
	v_fma_f32 v126, v126, v136, v98
	v_fma_f32 v129, v129, v136, v101
	v_mul_f32_e32 v119, 0xbfb8aa3b, v119
	v_med3_f32 v116, v116, s51, v169
	v_med3_f32 v126, v126, s51, v169
	v_med3_f32 v129, v129, s51, v169
	v_exp_f32_e32 v119, v119
	v_mul_f32_e32 v116, 0xbfb8aa3b, v116
	v_mul_f32_e32 v126, 0xbfb8aa3b, v126
	v_mul_f32_e32 v129, 0xbfb8aa3b, v129
	v_exp_f32_e32 v116, v116
	v_exp_f32_e32 v126, v126
	v_exp_f32_e32 v129, v129
	v_fma_f32 v117, v117, v136, v89
	v_fma_f32 v122, v122, v136, v106
	v_fma_f32 v125, v125, v136, v109
	v_med3_f32 v117, v117, s51, v169
	v_med3_f32 v122, v122, s51, v169
	v_med3_f32 v125, v125, s51, v169
	v_add_f32_e32 v114, 1.0, v119
	v_mul_f32_e32 v117, 0xbfb8aa3b, v117
	v_mul_f32_e32 v122, 0xbfb8aa3b, v122
	v_mul_f32_e32 v125, 0xbfb8aa3b, v125
	v_rcp_f32_e32 v114, v114
	v_exp_f32_e32 v117, v117
	v_add_f32_e32 v116, 1.0, v116
	v_exp_f32_e32 v122, v122
	v_exp_f32_e32 v125, v125
	v_add_f32_e32 v126, 1.0, v126
	v_add_f32_e32 v129, 1.0, v129
	v_rcp_f32_e32 v116, v116
	v_rcp_f32_e32 v126, v126
	v_rcp_f32_e32 v129, v129
	v_mul_f32_e32 v119, v115, v114
	v_add_f32_e32 v114, 1.0, v117
	v_lshl_add_u64 v[134:135], v[132:133], 0, s[58:59]
	v_add_f32_e32 v122, 1.0, v122
	v_add_f32_e32 v125, 1.0, v125
	v_mul_f32_e32 v117, v114, v116
	v_rcp_f32_e32 v137, v122
	v_mul_f32_e32 v122, v122, v126
	v_rcp_f32_e32 v126, v125
	v_mul_f32_e32 v125, v125, v129
	v_rcp_f32_e32 v129, v115
	v_rcp_f32_e32 v121, v114
	v_cvt_pk_bf16_f32 v114, v122, v123
	v_cvt_pk_bf16_f32 v115, v124, v125
	v_cvt_pk_bf16_f32 v116, v118, v128
	v_cvt_pk_bf16_f32 v117, v119, v117
	v_lshl_add_u64 v[118:119], s[18:19], 0, v[134:135]
	v_lshl_add_u64 v[118:119], v[118:119], 0, v[130:131]
	global_store_dwordx4 v[118:119], v[114:117], off
	v_lshl_add_u64 v[118:119], s[20:21], 0, v[134:135]
	v_lshl_add_u64 v[118:119], v[118:119], 0, v[130:131]
	v_cvt_pk_bf16_f32 v114, v137, v138
	v_cvt_pk_bf16_f32 v115, v139, v126
	v_cvt_pk_bf16_f32 v116, v127, v120
	v_cvt_pk_bf16_f32 v117, v129, v121
	global_store_dwordx4 v[118:119], v[114:117], off
	s_nop 1
	v_mov_b32_e32 v116, v223
	s_mov_b64 s[58:59], 0x80000
	v_lshl_add_u64 v[114:115], v[132:133], 0, s[28:29]
	v_fma_f32 v110, v110, v116, v98
	v_med3_f32 v110, v110, s51, v169
	v_fma_f32 v111, v111, v116, v99
	v_mul_f32_e32 v110, 0xbfb8aa3b, v110
	v_med3_f32 v111, v111, s51, v169
	v_exp_f32_e32 v110, v110
	v_fma_f32 v102, v102, v116, v106
	v_mul_f32_e32 v111, 0xbfb8aa3b, v111
	v_med3_f32 v102, v102, s51, v169
	v_exp_f32_e32 v111, v111
	v_fma_f32 v103, v103, v116, v107
	v_mul_f32_e32 v102, 0xbfb8aa3b, v102
	v_med3_f32 v103, v103, s51, v169
	v_exp_f32_e32 v102, v102
	v_add_f32_e32 v110, 1.0, v110
	v_mul_f32_e32 v103, 0xbfb8aa3b, v103
	v_rcp_f32_e32 v110, v110
	v_fma_f32 v112, v112, v116, v100
	v_exp_f32_e32 v103, v103
	v_add_f32_e32 v111, 1.0, v111
	v_med3_f32 v112, v112, s51, v169
	v_rcp_f32_e32 v111, v111
	v_mul_f32_e32 v112, 0xbfb8aa3b, v112
	v_add_f32_e32 v102, 1.0, v102
	v_rcp_f32_e32 v117, v102
	v_mul_f32_e32 v102, v102, v110
	v_exp_f32_e32 v110, v112
	v_fma_f32 v104, v104, v116, v108
	v_add_f32_e32 v103, 1.0, v103
	v_med3_f32 v104, v104, s51, v169
	v_rcp_f32_e32 v112, v103
	v_mul_f32_e32 v103, v103, v111
	v_fma_f32 v111, v113, v116, v101
	v_fma_f32 v94, v94, v116, v90
	v_mul_f32_e32 v104, 0xbfb8aa3b, v104
	v_med3_f32 v111, v111, s51, v169
	v_med3_f32 v94, v94, s51, v169
	v_exp_f32_e32 v104, v104
	v_add_f32_e32 v110, 1.0, v110
	v_mul_f32_e32 v111, 0xbfb8aa3b, v111
	v_mul_f32_e32 v94, 0xbfb8aa3b, v94
	v_rcp_f32_e32 v110, v110
	v_exp_f32_e32 v111, v111
	v_exp_f32_e32 v94, v94
	v_fma_f32 v105, v105, v116, v109
	v_fma_f32 v82, v82, v116, v86
	v_med3_f32 v105, v105, s51, v169
	v_med3_f32 v82, v82, s51, v169
	v_fma_f32 v95, v95, v116, v91
	v_add_f32_e32 v104, 1.0, v104
	v_mul_f32_e32 v105, 0xbfb8aa3b, v105
	v_mul_f32_e32 v82, 0xbfb8aa3b, v82
	v_med3_f32 v95, v95, s51, v169
	v_exp_f32_e32 v105, v105
	v_rcp_f32_e32 v113, v104
	v_mul_f32_e32 v104, v104, v110
	v_add_f32_e32 v110, 1.0, v111
	v_exp_f32_e32 v82, v82
	v_add_f32_e32 v94, 1.0, v94
	v_mul_f32_e32 v95, 0xbfb8aa3b, v95
	v_rcp_f32_e32 v110, v110
	v_rcp_f32_e32 v94, v94
	v_exp_f32_e32 v95, v95
	v_fma_f32 v83, v83, v116, v87
	v_med3_f32 v83, v83, s51, v169
	v_fma_f32 v84, v84, v116, v88
	v_add_f32_e32 v105, 1.0, v105
	v_add_f32_e32 v82, 1.0, v82
	v_mul_f32_e32 v83, 0xbfb8aa3b, v83
	v_med3_f32 v84, v84, s51, v169
	v_rcp_f32_e32 v111, v105
	v_mul_f32_e32 v105, v105, v110
	v_exp_f32_e32 v83, v83
	v_rcp_f32_e32 v110, v82
	v_mul_f32_e32 v94, v82, v94
	v_add_f32_e32 v82, 1.0, v95
	v_mul_f32_e32 v84, 0xbfb8aa3b, v84
	v_rcp_f32_e32 v82, v82
	v_exp_f32_e32 v84, v84
	v_add_f32_e32 v83, 1.0, v83
	v_fma_f32 v95, v96, v116, v92
	v_med3_f32 v95, v95, s51, v169
	v_rcp_f32_e32 v96, v83
	v_mul_f32_e32 v118, v83, v82
	v_add_f32_e32 v83, 1.0, v84
	v_fma_f32 v84, v97, v116, v93
	v_mul_f32_e32 v95, 0xbfb8aa3b, v95
	v_med3_f32 v84, v84, s51, v169
	v_exp_f32_e32 v95, v95
	v_mul_f32_e32 v84, 0xbfb8aa3b, v84
	v_exp_f32_e32 v84, v84
	v_fma_f32 v85, v85, v116, v89
	v_med3_f32 v85, v85, s51, v169
	v_add_f32_e32 v82, 1.0, v95
	v_mul_f32_e32 v85, 0xbfb8aa3b, v85
	v_rcp_f32_e32 v82, v82
	v_exp_f32_e32 v85, v85
	v_add_f32_e32 v84, 1.0, v84
	v_rcp_f32_e32 v84, v84
	v_mul_f32_e32 v95, v83, v82
	v_add_f32_e32 v82, 1.0, v85
	v_rcp_f32_e32 v119, v83
	v_mul_f32_e32 v85, v82, v84
	v_rcp_f32_e32 v97, v82
	v_cvt_pk_bf16_f32 v82, v102, v103
	v_cvt_pk_bf16_f32 v83, v104, v105
	v_cvt_pk_bf16_f32 v84, v94, v118
	v_cvt_pk_bf16_f32 v85, v95, v85
	v_lshl_add_u64 v[94:95], s[18:19], 0, v[114:115]
	v_lshl_add_u64 v[94:95], v[94:95], 0, v[130:131]
	global_store_dwordx4 v[94:95], v[82:85], off
	v_lshl_add_u64 v[94:95], s[20:21], 0, v[114:115]
	v_lshl_add_u64 v[94:95], v[94:95], 0, v[130:131]
	v_cvt_pk_bf16_f32 v82, v117, v112
	v_cvt_pk_bf16_f32 v83, v113, v111
	v_cvt_pk_bf16_f32 v84, v110, v96
	v_cvt_pk_bf16_f32 v85, v119, v97
	global_store_dwordx4 v[94:95], v[82:85], off
	s_nop 1
	v_mov_b32_e32 v84, v224
	v_fma_f32 v78, v78, v84, v98
	v_med3_f32 v78, v78, s51, v169
	v_mul_f32_e32 v78, 0xbfb8aa3b, v78
	v_exp_f32_e32 v78, v78
	v_fma_f32 v74, v74, v84, v106
	v_med3_f32 v74, v74, s51, v169
	v_fma_f32 v79, v79, v84, v99
	v_mul_f32_e32 v74, 0xbfb8aa3b, v74
	v_med3_f32 v79, v79, s51, v169
	v_exp_f32_e32 v74, v74
	v_add_f32_e32 v78, 1.0, v78
	v_mul_f32_e32 v79, 0xbfb8aa3b, v79
	v_rcp_f32_e32 v78, v78
	v_exp_f32_e32 v79, v79
	v_add_f32_e32 v74, 1.0, v74
	v_fma_f32 v75, v75, v84, v107
	v_med3_f32 v75, v75, s51, v169
	v_rcp_f32_e32 v85, v74
	v_mul_f32_e32 v74, v74, v78
	v_add_f32_e32 v78, 1.0, v79
	v_fma_f32 v79, v80, v84, v100
	v_mul_f32_e32 v75, 0xbfb8aa3b, v75
	v_med3_f32 v79, v79, s51, v169
	v_exp_f32_e32 v75, v75
	v_mul_f32_e32 v79, 0xbfb8aa3b, v79
	v_rcp_f32_e32 v78, v78
	v_exp_f32_e32 v79, v79
	v_add_f32_e32 v75, 1.0, v75
	v_fma_f32 v76, v76, v84, v108
	v_med3_f32 v76, v76, s51, v169
	v_rcp_f32_e32 v80, v75
	v_mul_f32_e32 v75, v75, v78
	v_add_f32_e32 v78, 1.0, v79
	v_fma_f32 v79, v81, v84, v101
	v_fma_f32 v70, v70, v84, v90
	v_mul_f32_e32 v76, 0xbfb8aa3b, v76
	v_med3_f32 v79, v79, s51, v169
	v_med3_f32 v70, v70, s51, v169
	v_exp_f32_e32 v76, v76
	v_mul_f32_e32 v79, 0xbfb8aa3b, v79
	v_mul_f32_e32 v70, 0xbfb8aa3b, v70
	v_rcp_f32_e32 v78, v78
	v_exp_f32_e32 v79, v79
	v_exp_f32_e32 v70, v70
	v_fma_f32 v77, v77, v84, v109
	v_fma_f32 v66, v66, v84, v86
	v_med3_f32 v77, v77, s51, v169
	v_med3_f32 v66, v66, s51, v169
	v_fma_f32 v71, v71, v84, v91
	v_add_f32_e32 v76, 1.0, v76
	v_mul_f32_e32 v77, 0xbfb8aa3b, v77
	v_mul_f32_e32 v66, 0xbfb8aa3b, v66
	v_med3_f32 v71, v71, s51, v169
	v_exp_f32_e32 v77, v77
	v_rcp_f32_e32 v81, v76
	v_mul_f32_e32 v76, v76, v78
	v_add_f32_e32 v78, 1.0, v79
	v_exp_f32_e32 v66, v66
	v_add_f32_e32 v70, 1.0, v70
	v_mul_f32_e32 v71, 0xbfb8aa3b, v71
	v_rcp_f32_e32 v78, v78
	v_rcp_f32_e32 v70, v70
	v_exp_f32_e32 v71, v71
	v_fma_f32 v67, v67, v84, v87
	v_med3_f32 v67, v67, s51, v169
	v_fma_f32 v68, v68, v84, v88
	v_add_f32_e32 v77, 1.0, v77
	v_add_f32_e32 v66, 1.0, v66
	v_mul_f32_e32 v67, 0xbfb8aa3b, v67
	v_med3_f32 v68, v68, s51, v169
	v_rcp_f32_e32 v79, v77
	v_mul_f32_e32 v77, v77, v78
	v_exp_f32_e32 v67, v67
	v_rcp_f32_e32 v78, v66
	v_mul_f32_e32 v70, v66, v70
	v_add_f32_e32 v66, 1.0, v71
	v_mul_f32_e32 v68, 0xbfb8aa3b, v68
	v_rcp_f32_e32 v66, v66
	v_exp_f32_e32 v68, v68
	v_add_f32_e32 v67, 1.0, v67
	v_fma_f32 v71, v72, v84, v92
	v_med3_f32 v71, v71, s51, v169
	v_rcp_f32_e32 v72, v67
	v_mul_f32_e32 v94, v67, v66
	v_add_f32_e32 v67, 1.0, v68
	v_fma_f32 v68, v73, v84, v93
	v_mul_f32_e32 v71, 0xbfb8aa3b, v71
	v_med3_f32 v68, v68, s51, v169
	v_exp_f32_e32 v71, v71
	v_mul_f32_e32 v68, 0xbfb8aa3b, v68
	v_exp_f32_e32 v68, v68
	v_fma_f32 v69, v69, v84, v89
	v_med3_f32 v69, v69, s51, v169
	v_add_f32_e32 v66, 1.0, v71
	v_mul_f32_e32 v69, 0xbfb8aa3b, v69
	v_rcp_f32_e32 v66, v66
	v_exp_f32_e32 v69, v69
	v_add_f32_e32 v68, 1.0, v68
	v_rcp_f32_e32 v68, v68
	v_mul_f32_e32 v71, v67, v66
	v_add_f32_e32 v66, 1.0, v69
	v_lshl_add_u64 v[82:83], v[132:133], 0, s[30:31]
	v_mul_f32_e32 v69, v66, v68
	v_rcp_f32_e32 v95, v67
	v_rcp_f32_e32 v73, v66
	v_cvt_pk_bf16_f32 v66, v74, v75
	v_cvt_pk_bf16_f32 v67, v76, v77
	v_cvt_pk_bf16_f32 v68, v70, v94
	v_cvt_pk_bf16_f32 v69, v71, v69
	v_lshl_add_u64 v[70:71], s[18:19], 0, v[82:83]
	v_lshl_add_u64 v[70:71], v[70:71], 0, v[130:131]
	global_store_dwordx4 v[70:71], v[66:69], off
	v_lshl_add_u64 v[70:71], s[20:21], 0, v[82:83]
	v_lshl_add_u64 v[70:71], v[70:71], 0, v[130:131]
	v_cvt_pk_bf16_f32 v66, v85, v80
	v_cvt_pk_bf16_f32 v67, v81, v79
	v_cvt_pk_bf16_f32 v68, v78, v72
	v_cvt_pk_bf16_f32 v69, v95, v73
	global_store_dwordx4 v[70:71], v[66:69], off
	s_nop 1
	v_mov_b32_e32 v68, v225
	v_fma_f32 v62, v62, v68, v98
	v_med3_f32 v62, v62, s51, v169
	v_mul_f32_e32 v62, 0xbfb8aa3b, v62
	v_exp_f32_e32 v62, v62
	v_fma_f32 v58, v58, v68, v106
	v_med3_f32 v58, v58, s51, v169
	v_fma_f32 v63, v63, v68, v99
	v_mul_f32_e32 v58, 0xbfb8aa3b, v58
	v_med3_f32 v63, v63, s51, v169
	v_exp_f32_e32 v58, v58
	v_add_f32_e32 v62, 1.0, v62
	v_mul_f32_e32 v63, 0xbfb8aa3b, v63
	v_rcp_f32_e32 v62, v62
	v_exp_f32_e32 v63, v63
	v_add_f32_e32 v58, 1.0, v58
	v_fma_f32 v59, v59, v68, v107
	v_med3_f32 v59, v59, s51, v169
	v_rcp_f32_e32 v69, v58
	v_mul_f32_e32 v58, v58, v62
	v_add_f32_e32 v62, 1.0, v63
	v_fma_f32 v63, v64, v68, v100
	v_mul_f32_e32 v59, 0xbfb8aa3b, v59
	v_med3_f32 v63, v63, s51, v169
	v_exp_f32_e32 v59, v59
	v_mul_f32_e32 v63, 0xbfb8aa3b, v63
	v_rcp_f32_e32 v62, v62
	v_exp_f32_e32 v63, v63
	v_add_f32_e32 v59, 1.0, v59
	v_fma_f32 v60, v60, v68, v108
	v_med3_f32 v60, v60, s51, v169
	v_rcp_f32_e32 v64, v59
	v_mul_f32_e32 v59, v59, v62
	v_add_f32_e32 v62, 1.0, v63
	v_fma_f32 v63, v65, v68, v101
	v_fma_f32 v54, v54, v68, v90
	v_mul_f32_e32 v60, 0xbfb8aa3b, v60
	v_med3_f32 v63, v63, s51, v169
	v_med3_f32 v54, v54, s51, v169
	v_exp_f32_e32 v60, v60
	v_mul_f32_e32 v63, 0xbfb8aa3b, v63
	v_mul_f32_e32 v54, 0xbfb8aa3b, v54
	v_rcp_f32_e32 v62, v62
	v_exp_f32_e32 v63, v63
	v_exp_f32_e32 v54, v54
	v_fma_f32 v61, v61, v68, v109
	v_fma_f32 v50, v50, v68, v86
	v_med3_f32 v61, v61, s51, v169
	v_med3_f32 v50, v50, s51, v169
	v_fma_f32 v55, v55, v68, v91
	v_add_f32_e32 v60, 1.0, v60
	v_mul_f32_e32 v61, 0xbfb8aa3b, v61
	v_mul_f32_e32 v50, 0xbfb8aa3b, v50
	v_med3_f32 v55, v55, s51, v169
	v_exp_f32_e32 v61, v61
	v_rcp_f32_e32 v65, v60
	v_mul_f32_e32 v60, v60, v62
	v_add_f32_e32 v62, 1.0, v63
	v_exp_f32_e32 v50, v50
	v_add_f32_e32 v54, 1.0, v54
	v_mul_f32_e32 v55, 0xbfb8aa3b, v55
	v_rcp_f32_e32 v62, v62
	v_rcp_f32_e32 v54, v54
	v_exp_f32_e32 v55, v55
	v_fma_f32 v51, v51, v68, v87
	v_med3_f32 v51, v51, s51, v169
	v_fma_f32 v52, v52, v68, v88
	v_add_f32_e32 v61, 1.0, v61
	v_add_f32_e32 v50, 1.0, v50
	v_mul_f32_e32 v51, 0xbfb8aa3b, v51
	v_med3_f32 v52, v52, s51, v169
	v_rcp_f32_e32 v63, v61
	v_mul_f32_e32 v61, v61, v62
	v_exp_f32_e32 v51, v51
	v_rcp_f32_e32 v62, v50
	v_mul_f32_e32 v54, v50, v54
	v_add_f32_e32 v50, 1.0, v55
	v_mul_f32_e32 v52, 0xbfb8aa3b, v52
	v_rcp_f32_e32 v50, v50
	v_exp_f32_e32 v52, v52
	v_add_f32_e32 v51, 1.0, v51
	v_fma_f32 v55, v56, v68, v92
	v_med3_f32 v55, v55, s51, v169
	v_rcp_f32_e32 v56, v51
	v_mul_f32_e32 v70, v51, v50
	v_add_f32_e32 v51, 1.0, v52
	v_fma_f32 v52, v57, v68, v93
	v_mul_f32_e32 v55, 0xbfb8aa3b, v55
	v_med3_f32 v52, v52, s51, v169
	v_exp_f32_e32 v55, v55
	v_mul_f32_e32 v52, 0xbfb8aa3b, v52
	v_exp_f32_e32 v52, v52
	v_fma_f32 v53, v53, v68, v89
	v_med3_f32 v53, v53, s51, v169
	v_add_f32_e32 v50, 1.0, v55
	v_mul_f32_e32 v53, 0xbfb8aa3b, v53
	v_rcp_f32_e32 v50, v50
	v_exp_f32_e32 v53, v53
	v_add_f32_e32 v52, 1.0, v52
	v_rcp_f32_e32 v52, v52
	v_mul_f32_e32 v55, v51, v50
	v_add_f32_e32 v50, 1.0, v53
	v_lshl_add_u64 v[66:67], v[132:133], 0, s[58:59]
	v_mul_f32_e32 v53, v50, v52
	v_rcp_f32_e32 v71, v51
	v_rcp_f32_e32 v57, v50
	v_cvt_pk_bf16_f32 v50, v58, v59
	v_cvt_pk_bf16_f32 v51, v60, v61
	v_cvt_pk_bf16_f32 v52, v54, v70
	v_cvt_pk_bf16_f32 v53, v55, v53
	v_lshl_add_u64 v[54:55], s[18:19], 0, v[66:67]
	v_lshl_add_u64 v[54:55], v[54:55], 0, v[130:131]
	global_store_dwordx4 v[54:55], v[50:53], off
	v_lshl_add_u64 v[54:55], s[20:21], 0, v[66:67]
	v_lshl_add_u64 v[54:55], v[54:55], 0, v[130:131]
	v_cvt_pk_bf16_f32 v50, v69, v64
	v_cvt_pk_bf16_f32 v51, v65, v63
	v_cvt_pk_bf16_f32 v52, v62, v56
	v_cvt_pk_bf16_f32 v53, v71, v57
	global_store_dwordx4 v[54:55], v[50:53], off
	s_nop 1
	v_mov_b32_e32 v52, v226
	v_fma_f32 v46, v46, v52, v98
	v_med3_f32 v46, v46, s51, v169
	v_mul_f32_e32 v46, 0xbfb8aa3b, v46
	v_exp_f32_e32 v46, v46
	v_fma_f32 v42, v42, v52, v106
	v_med3_f32 v42, v42, s51, v169
	v_fma_f32 v47, v47, v52, v99
	v_mul_f32_e32 v42, 0xbfb8aa3b, v42
	v_med3_f32 v47, v47, s51, v169
	v_exp_f32_e32 v42, v42
	v_add_f32_e32 v46, 1.0, v46
	v_mul_f32_e32 v47, 0xbfb8aa3b, v47
	v_rcp_f32_e32 v46, v46
	v_exp_f32_e32 v47, v47
	v_add_f32_e32 v42, 1.0, v42
	v_fma_f32 v43, v43, v52, v107
	v_med3_f32 v43, v43, s51, v169
	v_rcp_f32_e32 v53, v42
	v_mul_f32_e32 v42, v42, v46
	v_add_f32_e32 v46, 1.0, v47
	v_fma_f32 v47, v48, v52, v100
	v_mul_f32_e32 v43, 0xbfb8aa3b, v43
	v_med3_f32 v47, v47, s51, v169
	v_exp_f32_e32 v43, v43
	v_mul_f32_e32 v47, 0xbfb8aa3b, v47
	v_rcp_f32_e32 v46, v46
	v_exp_f32_e32 v47, v47
	v_add_f32_e32 v43, 1.0, v43
	v_fma_f32 v44, v44, v52, v108
	v_med3_f32 v44, v44, s51, v169
	v_rcp_f32_e32 v48, v43
	v_mul_f32_e32 v43, v43, v46
	v_add_f32_e32 v46, 1.0, v47
	v_fma_f32 v47, v49, v52, v101
	v_fma_f32 v38, v38, v52, v90
	v_mul_f32_e32 v44, 0xbfb8aa3b, v44
	v_med3_f32 v47, v47, s51, v169
	v_med3_f32 v38, v38, s51, v169
	v_exp_f32_e32 v44, v44
	v_mul_f32_e32 v47, 0xbfb8aa3b, v47
	v_mul_f32_e32 v38, 0xbfb8aa3b, v38
	v_rcp_f32_e32 v46, v46
	v_exp_f32_e32 v47, v47
	v_exp_f32_e32 v38, v38
	v_fma_f32 v45, v45, v52, v109
	v_fma_f32 v34, v34, v52, v86
	v_med3_f32 v45, v45, s51, v169
	v_med3_f32 v34, v34, s51, v169
	v_fma_f32 v39, v39, v52, v91
	v_add_f32_e32 v44, 1.0, v44
	v_mul_f32_e32 v45, 0xbfb8aa3b, v45
	v_mul_f32_e32 v34, 0xbfb8aa3b, v34
	v_med3_f32 v39, v39, s51, v169
	v_exp_f32_e32 v45, v45
	v_rcp_f32_e32 v49, v44
	v_mul_f32_e32 v44, v44, v46
	v_add_f32_e32 v46, 1.0, v47
	v_exp_f32_e32 v34, v34
	v_add_f32_e32 v38, 1.0, v38
	v_mul_f32_e32 v39, 0xbfb8aa3b, v39
	v_rcp_f32_e32 v46, v46
	v_rcp_f32_e32 v38, v38
	v_exp_f32_e32 v39, v39
	v_fma_f32 v35, v35, v52, v87
	v_med3_f32 v35, v35, s51, v169
	v_fma_f32 v36, v36, v52, v88
	v_add_f32_e32 v45, 1.0, v45
	v_add_f32_e32 v34, 1.0, v34
	v_mul_f32_e32 v35, 0xbfb8aa3b, v35
	v_med3_f32 v36, v36, s51, v169
	v_rcp_f32_e32 v47, v45
	v_mul_f32_e32 v45, v45, v46
	v_exp_f32_e32 v35, v35
	v_rcp_f32_e32 v46, v34
	v_mul_f32_e32 v38, v34, v38
	v_add_f32_e32 v34, 1.0, v39
	v_mul_f32_e32 v36, 0xbfb8aa3b, v36
	v_rcp_f32_e32 v34, v34
	v_exp_f32_e32 v36, v36
	v_add_f32_e32 v35, 1.0, v35
	v_fma_f32 v39, v40, v52, v92
	v_med3_f32 v39, v39, s51, v169
	v_rcp_f32_e32 v40, v35
	v_mul_f32_e32 v54, v35, v34
	v_add_f32_e32 v35, 1.0, v36
	v_fma_f32 v36, v41, v52, v93
	v_mul_f32_e32 v39, 0xbfb8aa3b, v39
	v_med3_f32 v36, v36, s51, v169
	v_exp_f32_e32 v39, v39
	v_mul_f32_e32 v36, 0xbfb8aa3b, v36
	v_exp_f32_e32 v36, v36
	v_fma_f32 v37, v37, v52, v89
	v_med3_f32 v37, v37, s51, v169
	v_add_f32_e32 v34, 1.0, v39
	v_mul_f32_e32 v37, 0xbfb8aa3b, v37
	v_rcp_f32_e32 v34, v34
	v_exp_f32_e32 v37, v37
	v_add_f32_e32 v36, 1.0, v36
	v_rcp_f32_e32 v36, v36
	v_mul_f32_e32 v39, v35, v34
	v_add_f32_e32 v34, 1.0, v37
	v_lshl_add_u64 v[50:51], v[132:133], 0, s[36:37]
	v_mul_f32_e32 v37, v34, v36
	v_rcp_f32_e32 v55, v35
	v_rcp_f32_e32 v41, v34
	v_cvt_pk_bf16_f32 v34, v42, v43
	v_cvt_pk_bf16_f32 v35, v44, v45
	v_cvt_pk_bf16_f32 v36, v38, v54
	v_cvt_pk_bf16_f32 v37, v39, v37
	v_lshl_add_u64 v[38:39], s[18:19], 0, v[50:51]
	v_lshl_add_u64 v[38:39], v[38:39], 0, v[130:131]
	global_store_dwordx4 v[38:39], v[34:37], off
	v_lshl_add_u64 v[38:39], s[20:21], 0, v[50:51]
	v_lshl_add_u64 v[38:39], v[38:39], 0, v[130:131]
	v_cvt_pk_bf16_f32 v34, v53, v48
	v_cvt_pk_bf16_f32 v35, v49, v47
	v_cvt_pk_bf16_f32 v36, v46, v40
	v_cvt_pk_bf16_f32 v37, v55, v41
	global_store_dwordx4 v[38:39], v[34:37], off
	s_nop 1
	v_mov_b32_e32 v36, v227
	v_fma_f32 v30, v30, v36, v98
	v_med3_f32 v30, v30, s51, v169
	v_mul_f32_e32 v30, 0xbfb8aa3b, v30
	v_exp_f32_e32 v30, v30
	v_fma_f32 v26, v26, v36, v106
	v_med3_f32 v26, v26, s51, v169
	v_fma_f32 v31, v31, v36, v99
	v_mul_f32_e32 v26, 0xbfb8aa3b, v26
	v_med3_f32 v31, v31, s51, v169
	v_exp_f32_e32 v26, v26
	v_add_f32_e32 v30, 1.0, v30
	v_mul_f32_e32 v31, 0xbfb8aa3b, v31
	v_rcp_f32_e32 v30, v30
	v_exp_f32_e32 v31, v31
	v_add_f32_e32 v26, 1.0, v26
	v_fma_f32 v27, v27, v36, v107
	v_med3_f32 v27, v27, s51, v169
	v_rcp_f32_e32 v37, v26
	v_mul_f32_e32 v26, v26, v30
	v_add_f32_e32 v30, 1.0, v31
	v_fma_f32 v31, v32, v36, v100
	v_mul_f32_e32 v27, 0xbfb8aa3b, v27
	v_med3_f32 v31, v31, s51, v169
	v_exp_f32_e32 v27, v27
	v_mul_f32_e32 v31, 0xbfb8aa3b, v31
	v_rcp_f32_e32 v30, v30
	v_exp_f32_e32 v31, v31
	v_add_f32_e32 v27, 1.0, v27
	v_fma_f32 v28, v28, v36, v108
	v_med3_f32 v28, v28, s51, v169
	v_rcp_f32_e32 v32, v27
	v_mul_f32_e32 v27, v27, v30
	v_add_f32_e32 v30, 1.0, v31
	v_fma_f32 v31, v33, v36, v101
	v_fma_f32 v22, v22, v36, v90
	v_mul_f32_e32 v28, 0xbfb8aa3b, v28
	v_med3_f32 v31, v31, s51, v169
	v_med3_f32 v22, v22, s51, v169
	v_exp_f32_e32 v28, v28
	v_mul_f32_e32 v31, 0xbfb8aa3b, v31
	v_mul_f32_e32 v22, 0xbfb8aa3b, v22
	v_rcp_f32_e32 v30, v30
	v_exp_f32_e32 v31, v31
	v_exp_f32_e32 v22, v22
	v_fma_f32 v29, v29, v36, v109
	v_fma_f32 v18, v18, v36, v86
	v_med3_f32 v29, v29, s51, v169
	v_med3_f32 v18, v18, s51, v169
	v_fma_f32 v23, v23, v36, v91
	v_add_f32_e32 v28, 1.0, v28
	v_mul_f32_e32 v29, 0xbfb8aa3b, v29
	v_mul_f32_e32 v18, 0xbfb8aa3b, v18
	v_med3_f32 v23, v23, s51, v169
	v_exp_f32_e32 v29, v29
	v_rcp_f32_e32 v33, v28
	v_mul_f32_e32 v28, v28, v30
	v_add_f32_e32 v30, 1.0, v31
	v_exp_f32_e32 v18, v18
	v_add_f32_e32 v22, 1.0, v22
	v_mul_f32_e32 v23, 0xbfb8aa3b, v23
	v_rcp_f32_e32 v30, v30
	v_rcp_f32_e32 v22, v22
	v_exp_f32_e32 v23, v23
	v_fma_f32 v19, v19, v36, v87
	v_med3_f32 v19, v19, s51, v169
	v_fma_f32 v20, v20, v36, v88
	v_add_f32_e32 v29, 1.0, v29
	v_add_f32_e32 v18, 1.0, v18
	v_mul_f32_e32 v19, 0xbfb8aa3b, v19
	v_med3_f32 v20, v20, s51, v169
	v_rcp_f32_e32 v31, v29
	v_mul_f32_e32 v29, v29, v30
	v_exp_f32_e32 v19, v19
	v_rcp_f32_e32 v30, v18
	v_mul_f32_e32 v22, v18, v22
	v_add_f32_e32 v18, 1.0, v23
	v_mul_f32_e32 v20, 0xbfb8aa3b, v20
	v_rcp_f32_e32 v18, v18
	v_exp_f32_e32 v20, v20
	v_add_f32_e32 v19, 1.0, v19
	v_fma_f32 v23, v24, v36, v92
	v_med3_f32 v23, v23, s51, v169
	v_rcp_f32_e32 v24, v19
	v_mul_f32_e32 v38, v19, v18
	v_add_f32_e32 v19, 1.0, v20
	v_fma_f32 v20, v25, v36, v93
	v_mul_f32_e32 v23, 0xbfb8aa3b, v23
	v_med3_f32 v20, v20, s51, v169
	v_exp_f32_e32 v23, v23
	v_mul_f32_e32 v20, 0xbfb8aa3b, v20
	v_exp_f32_e32 v20, v20
	v_fma_f32 v21, v21, v36, v89
	v_med3_f32 v21, v21, s51, v169
	v_add_f32_e32 v18, 1.0, v23
	v_mul_f32_e32 v21, 0xbfb8aa3b, v21
	v_rcp_f32_e32 v18, v18
	v_exp_f32_e32 v21, v21
	v_add_f32_e32 v20, 1.0, v20
	v_rcp_f32_e32 v20, v20
	v_mul_f32_e32 v23, v19, v18
	v_add_f32_e32 v18, 1.0, v21
	v_lshl_add_u64 v[34:35], v[132:133], 0, s[40:41]
	v_mul_f32_e32 v21, v18, v20
	v_rcp_f32_e32 v39, v19
	v_rcp_f32_e32 v25, v18
	v_cvt_pk_bf16_f32 v18, v26, v27
	v_cvt_pk_bf16_f32 v19, v28, v29
	v_cvt_pk_bf16_f32 v20, v22, v38
	v_cvt_pk_bf16_f32 v21, v23, v21
	v_lshl_add_u64 v[22:23], s[18:19], 0, v[34:35]
	v_lshl_add_u64 v[22:23], v[22:23], 0, v[130:131]
	global_store_dwordx4 v[22:23], v[18:21], off
	v_lshl_add_u64 v[22:23], s[20:21], 0, v[34:35]
	v_lshl_add_u64 v[22:23], v[22:23], 0, v[130:131]
	v_cvt_pk_bf16_f32 v18, v37, v32
	v_cvt_pk_bf16_f32 v19, v33, v31
	v_cvt_pk_bf16_f32 v20, v30, v24
	v_cvt_pk_bf16_f32 v21, v39, v25
	global_store_dwordx4 v[22:23], v[18:21], off
	s_nop 1
	v_mov_b32_e32 v20, v228
	v_fma_f32 v14, v14, v20, v98
	v_med3_f32 v14, v14, s51, v169
	v_mul_f32_e32 v14, 0xbfb8aa3b, v14
	v_exp_f32_e32 v14, v14
	v_fma_f32 v10, v10, v20, v106
	v_med3_f32 v10, v10, s51, v169
	v_fma_f32 v15, v15, v20, v99
	v_mul_f32_e32 v10, 0xbfb8aa3b, v10
	v_med3_f32 v15, v15, s51, v169
	v_exp_f32_e32 v10, v10
	v_add_f32_e32 v14, 1.0, v14
	v_mul_f32_e32 v15, 0xbfb8aa3b, v15
	v_rcp_f32_e32 v14, v14
	v_exp_f32_e32 v15, v15
	v_add_f32_e32 v10, 1.0, v10
	v_fma_f32 v11, v11, v20, v107
	v_med3_f32 v11, v11, s51, v169
	v_rcp_f32_e32 v21, v10
	v_mul_f32_e32 v10, v10, v14
	v_add_f32_e32 v14, 1.0, v15
	v_fma_f32 v15, v16, v20, v100
	v_mul_f32_e32 v11, 0xbfb8aa3b, v11
	v_med3_f32 v15, v15, s51, v169
	v_exp_f32_e32 v11, v11
	v_mul_f32_e32 v15, 0xbfb8aa3b, v15
	v_rcp_f32_e32 v14, v14
	v_exp_f32_e32 v15, v15
	v_fma_f32 v12, v12, v20, v108
	v_add_f32_e32 v11, 1.0, v11
	v_med3_f32 v12, v12, s51, v169
	v_fmac_f32_e32 v101, v17, v20
	v_fma_f32 v6, v6, v20, v90
	v_mul_f32_e32 v12, 0xbfb8aa3b, v12
	v_rcp_f32_e32 v16, v11
	v_mul_f32_e32 v11, v11, v14
	v_add_f32_e32 v14, 1.0, v15
	v_med3_f32 v15, v101, s51, v169
	v_med3_f32 v6, v6, s51, v169
	v_exp_f32_e32 v12, v12
	v_mul_f32_e32 v15, 0xbfb8aa3b, v15
	v_mul_f32_e32 v6, 0xbfb8aa3b, v6
	v_rcp_f32_e32 v14, v14
	v_exp_f32_e32 v15, v15
	v_exp_f32_e32 v6, v6
	v_fmac_f32_e32 v109, v13, v20
	v_fma_f32 v2, v2, v20, v86
	v_med3_f32 v13, v109, s51, v169
	v_med3_f32 v2, v2, s51, v169
	v_fma_f32 v7, v7, v20, v91
	v_add_f32_e32 v12, 1.0, v12
	v_mul_f32_e32 v13, 0xbfb8aa3b, v13
	v_mul_f32_e32 v2, 0xbfb8aa3b, v2
	v_med3_f32 v7, v7, s51, v169
	v_exp_f32_e32 v13, v13
	v_rcp_f32_e32 v17, v12
	v_mul_f32_e32 v12, v12, v14
	v_add_f32_e32 v14, 1.0, v15
	v_exp_f32_e32 v2, v2
	v_add_f32_e32 v6, 1.0, v6
	v_mul_f32_e32 v7, 0xbfb8aa3b, v7
	v_rcp_f32_e32 v14, v14
	v_rcp_f32_e32 v6, v6
	v_exp_f32_e32 v7, v7
	v_fma_f32 v3, v3, v20, v87
	v_med3_f32 v3, v3, s51, v169
	v_fma_f32 v4, v4, v20, v88
	v_add_f32_e32 v13, 1.0, v13
	v_add_f32_e32 v2, 1.0, v2
	v_mul_f32_e32 v3, 0xbfb8aa3b, v3
	v_med3_f32 v4, v4, s51, v169
	v_rcp_f32_e32 v15, v13
	v_mul_f32_e32 v13, v13, v14
	v_exp_f32_e32 v3, v3
	v_rcp_f32_e32 v14, v2
	v_mul_f32_e32 v6, v2, v6
	v_add_f32_e32 v2, 1.0, v7
	v_mul_f32_e32 v4, 0xbfb8aa3b, v4
	v_rcp_f32_e32 v2, v2
	v_exp_f32_e32 v4, v4
	v_fma_f32 v7, v8, v20, v92
	v_add_f32_e32 v3, 1.0, v3
	v_med3_f32 v7, v7, s51, v169
	v_fmac_f32_e32 v93, v9, v20
	v_mul_f32_e32 v7, 0xbfb8aa3b, v7
	v_rcp_f32_e32 v8, v3
	v_mul_f32_e32 v22, v3, v2
	v_add_f32_e32 v3, 1.0, v4
	v_med3_f32 v4, v93, s51, v169
	v_exp_f32_e32 v7, v7
	v_mul_f32_e32 v4, 0xbfb8aa3b, v4
	v_exp_f32_e32 v4, v4
	v_fmac_f32_e32 v89, v5, v20
	v_med3_f32 v5, v89, s51, v169
	v_add_f32_e32 v2, 1.0, v7
	v_mul_f32_e32 v5, 0xbfb8aa3b, v5
	v_rcp_f32_e32 v2, v2
	v_exp_f32_e32 v5, v5
	v_add_f32_e32 v4, 1.0, v4
	v_rcp_f32_e32 v4, v4
	v_mul_f32_e32 v7, v3, v2
	v_add_f32_e32 v2, 1.0, v5
	v_lshl_add_u64 v[18:19], v[132:133], 0, s[42:43]
	v_mul_f32_e32 v5, v2, v4
	v_rcp_f32_e32 v23, v3
	v_rcp_f32_e32 v9, v2
	v_cvt_pk_bf16_f32 v2, v10, v11
	v_cvt_pk_bf16_f32 v3, v12, v13
	v_cvt_pk_bf16_f32 v4, v6, v22
	v_cvt_pk_bf16_f32 v5, v7, v5
	v_lshl_add_u64 v[6:7], s[18:19], 0, v[18:19]
	v_lshl_add_u64 v[6:7], v[6:7], 0, v[130:131]
	global_store_dwordx4 v[6:7], v[2:5], off
	v_lshl_add_u64 v[6:7], s[20:21], 0, v[18:19]
	v_lshl_add_u64 v[6:7], v[6:7], 0, v[130:131]
	v_cvt_pk_bf16_f32 v2, v21, v16
	v_cvt_pk_bf16_f32 v3, v17, v15
	v_cvt_pk_bf16_f32 v4, v14, v8
	v_cvt_pk_bf16_f32 v5, v23, v9
	global_store_dwordx4 v[6:7], v[2:5], off
	s_cbranch_vccnz .LBB0_1126
	s_andn2_b64 vcc, exec, s[8:9]
	s_cbranch_vccnz .LBB0_1125
	s_barrier
	s_branch .LBB0_1125

.LBB0_1528:
	v_mov_b32_e32 v146, v1
	v_mov_b32_e32 v155, v150
	s_lshl_b32 s31, s42, 8
	s_add_i32 s31, s31, s54
	v_add_u32_e32 v146, s31, v146
	v_ashrrev_i32_e32 v147, 31, v146
	v_lshl_add_u64 v[148:149], v[146:147], 2, s[8:9]
	global_load_dword v158, v[148:149], off
	global_load_dword v222, v[148:149], off offset:64
	global_load_dword v223, v[148:149], off offset:128
	global_load_dword v224, v[148:149], off offset:192
	global_load_dword v225, v[148:149], off offset:512
	global_load_dword v226, v[148:149], off offset:576
	global_load_dword v227, v[148:149], off offset:640
	global_load_dword v228, v[148:149], off offset:704
	s_lshl_b32 s31, s68, 8
	s_or_b32 s31, s31, s55
	v_lshl_add_u32 v156, v155, 3, s31
	v_lshlrev_b64 v[146:147], 10, v[146:147]
	v_ashrrev_i32_e32 v157, 31, v156
	v_lshl_add_u64 v[146:147], s[10:11], 0, v[146:147]
	v_lshl_add_u64 v[146:147], v[156:157], 1, v[146:147]
	s_waitcnt vmcnt(0)
	v_mul_f32_e32 v156, 0x3e0293ee, v158
	v_pk_mul_f32 v[128:129], v[128:129], v[156:157] op_sel_hi:[1,0]
	v_pk_mul_f32 v[126:127], v[126:127], v[156:157] op_sel_hi:[1,0]
	v_pk_mul_f32 v[124:125], v[124:125], v[156:157] op_sel_hi:[1,0]
	v_pk_mul_f32 v[122:123], v[122:123], v[156:157] op_sel_hi:[1,0]
	v_pk_mul_f32 v[120:121], v[120:121], v[156:157] op_sel_hi:[1,0]
	v_pk_mul_f32 v[118:119], v[118:119], v[156:157] op_sel_hi:[1,0]
	v_pk_mul_f32 v[158:159], v[116:117], v[156:157] op_sel_hi:[1,0]
	v_pk_mul_f32 v[156:157], v[114:115], v[156:157] op_sel_hi:[1,0]
	v_cvt_pk_bf16_f32 v114, v126, v127
	v_cvt_pk_bf16_f32 v115, v128, v129
	v_cvt_pk_bf16_f32 v116, v122, v123
	v_cvt_pk_bf16_f32 v117, v124, v125
	global_store_dwordx4 v[146:147], v[114:117], off
	s_nop 1
	v_cvt_pk_bf16_f32 v114, v118, v119
	v_cvt_pk_bf16_f32 v115, v120, v121
	v_cvt_pk_bf16_f32 v116, v156, v157
	v_cvt_pk_bf16_f32 v117, v158, v159
	global_store_dwordx4 v[146:147], v[114:117], off offset:256
	s_nop 1
	v_mov_b32_e32 v118, v222
	v_mul_f32_e32 v118, 0x3e0293ee, v118
	v_add_co_u32_e32 v116, vcc, s53, v146
	v_lshl_add_u64 v[114:115], v[146:147], 0, s[16:17]
	s_nop 0
	v_addc_co_u32_e32 v117, vcc, 0, v147, vcc
	v_pk_mul_f32 v[112:113], v[112:113], v[118:119] op_sel_hi:[1,0]
	v_pk_mul_f32 v[110:111], v[110:111], v[118:119] op_sel_hi:[1,0]
	v_pk_mul_f32 v[108:109], v[108:109], v[118:119] op_sel_hi:[1,0]
	v_pk_mul_f32 v[106:107], v[106:107], v[118:119] op_sel_hi:[1,0]
	v_pk_mul_f32 v[104:105], v[104:105], v[118:119] op_sel_hi:[1,0]
	v_pk_mul_f32 v[102:103], v[102:103], v[118:119] op_sel_hi:[1,0]
	v_pk_mul_f32 v[120:121], v[100:101], v[118:119] op_sel_hi:[1,0]
	v_pk_mul_f32 v[118:119], v[98:99], v[118:119] op_sel_hi:[1,0]
	v_cvt_pk_bf16_f32 v98, v110, v111
	v_cvt_pk_bf16_f32 v99, v112, v113
	v_cvt_pk_bf16_f32 v100, v106, v107
	v_cvt_pk_bf16_f32 v101, v108, v109
	global_store_dwordx4 v[116:117], v[98:101], off
	s_nop 1
	v_cvt_pk_bf16_f32 v98, v102, v103
	v_cvt_pk_bf16_f32 v99, v104, v105
	v_cvt_pk_bf16_f32 v100, v118, v119
	v_cvt_pk_bf16_f32 v101, v120, v121
	global_store_dwordx4 v[114:115], v[98:101], off offset:256
	s_nop 1
	v_mov_b32_e32 v102, v223
	v_mul_f32_e32 v102, 0x3e0293ee, v102
	v_add_co_u32_e32 v100, vcc, s59, v146
	v_lshl_add_u64 v[98:99], v[146:147], 0, s[18:19]
	s_nop 0
	v_addc_co_u32_e32 v101, vcc, 0, v147, vcc
	v_pk_mul_f32 v[96:97], v[96:97], v[102:103] op_sel_hi:[1,0]
	v_pk_mul_f32 v[94:95], v[94:95], v[102:103] op_sel_hi:[1,0]
	v_pk_mul_f32 v[92:93], v[92:93], v[102:103] op_sel_hi:[1,0]
	v_pk_mul_f32 v[90:91], v[90:91], v[102:103] op_sel_hi:[1,0]
	v_pk_mul_f32 v[88:89], v[88:89], v[102:103] op_sel_hi:[1,0]
	v_pk_mul_f32 v[86:87], v[86:87], v[102:103] op_sel_hi:[1,0]
	v_pk_mul_f32 v[104:105], v[84:85], v[102:103] op_sel_hi:[1,0]
	v_pk_mul_f32 v[102:103], v[82:83], v[102:103] op_sel_hi:[1,0]
	v_cvt_pk_bf16_f32 v82, v94, v95
	v_cvt_pk_bf16_f32 v83, v96, v97
	v_cvt_pk_bf16_f32 v84, v90, v91
	v_cvt_pk_bf16_f32 v85, v92, v93
	global_store_dwordx4 v[100:101], v[82:85], off
	s_nop 1
	v_cvt_pk_bf16_f32 v82, v86, v87
	v_cvt_pk_bf16_f32 v83, v88, v89
	v_cvt_pk_bf16_f32 v84, v102, v103
	v_cvt_pk_bf16_f32 v85, v104, v105
	global_store_dwordx4 v[98:99], v[82:85], off offset:256
	s_nop 1
	v_mov_b32_e32 v86, v224
	v_mul_f32_e32 v86, 0x3e0293ee, v86
	v_add_co_u32_e32 v84, vcc, s63, v146
	v_lshl_add_u64 v[82:83], v[146:147], 0, s[20:21]
	s_nop 0
	v_addc_co_u32_e32 v85, vcc, 0, v147, vcc
	v_pk_mul_f32 v[80:81], v[80:81], v[86:87] op_sel_hi:[1,0]
	v_pk_mul_f32 v[78:79], v[78:79], v[86:87] op_sel_hi:[1,0]
	v_pk_mul_f32 v[76:77], v[76:77], v[86:87] op_sel_hi:[1,0]
	v_pk_mul_f32 v[74:75], v[74:75], v[86:87] op_sel_hi:[1,0]
	v_pk_mul_f32 v[72:73], v[72:73], v[86:87] op_sel_hi:[1,0]
	v_pk_mul_f32 v[70:71], v[70:71], v[86:87] op_sel_hi:[1,0]
	v_pk_mul_f32 v[88:89], v[68:69], v[86:87] op_sel_hi:[1,0]
	v_pk_mul_f32 v[86:87], v[66:67], v[86:87] op_sel_hi:[1,0]
	v_cvt_pk_bf16_f32 v66, v78, v79
	v_cvt_pk_bf16_f32 v67, v80, v81
	v_cvt_pk_bf16_f32 v68, v74, v75
	v_cvt_pk_bf16_f32 v69, v76, v77
	global_store_dwordx4 v[84:85], v[66:69], off
	s_nop 1
	v_cvt_pk_bf16_f32 v66, v70, v71
	v_cvt_pk_bf16_f32 v67, v72, v73
	v_cvt_pk_bf16_f32 v68, v86, v87
	v_cvt_pk_bf16_f32 v69, v88, v89
	global_store_dwordx4 v[82:83], v[66:69], off offset:256
	s_nop 1
	v_mov_b32_e32 v70, v225
	v_mul_f32_e32 v70, 0x3e0293ee, v70
	v_add_co_u32_e32 v68, vcc, s64, v146
	v_lshl_add_u64 v[66:67], v[146:147], 0, s[22:23]
	s_nop 0
	v_addc_co_u32_e32 v69, vcc, 0, v147, vcc
	v_pk_mul_f32 v[64:65], v[64:65], v[70:71] op_sel_hi:[1,0]
	v_pk_mul_f32 v[62:63], v[62:63], v[70:71] op_sel_hi:[1,0]
	v_pk_mul_f32 v[60:61], v[60:61], v[70:71] op_sel_hi:[1,0]
	v_pk_mul_f32 v[58:59], v[58:59], v[70:71] op_sel_hi:[1,0]
	v_pk_mul_f32 v[56:57], v[56:57], v[70:71] op_sel_hi:[1,0]
	v_pk_mul_f32 v[54:55], v[54:55], v[70:71] op_sel_hi:[1,0]
	v_pk_mul_f32 v[72:73], v[52:53], v[70:71] op_sel_hi:[1,0]
	v_pk_mul_f32 v[70:71], v[50:51], v[70:71] op_sel_hi:[1,0]
	v_cvt_pk_bf16_f32 v50, v62, v63
	v_cvt_pk_bf16_f32 v51, v64, v65
	v_cvt_pk_bf16_f32 v52, v58, v59
	v_cvt_pk_bf16_f32 v53, v60, v61
	global_store_dwordx4 v[68:69], v[50:53], off
	s_nop 1
	v_cvt_pk_bf16_f32 v50, v54, v55
	v_cvt_pk_bf16_f32 v51, v56, v57
	v_cvt_pk_bf16_f32 v52, v70, v71
	v_cvt_pk_bf16_f32 v53, v72, v73
	global_store_dwordx4 v[66:67], v[50:53], off offset:256
	s_nop 1
	v_mov_b32_e32 v54, v226
	v_mul_f32_e32 v54, 0x3e0293ee, v54
	v_add_co_u32_e32 v52, vcc, s65, v146
	v_lshl_add_u64 v[50:51], v[146:147], 0, s[24:25]
	s_nop 0
	v_addc_co_u32_e32 v53, vcc, 0, v147, vcc
	v_pk_mul_f32 v[48:49], v[48:49], v[54:55] op_sel_hi:[1,0]
	v_pk_mul_f32 v[46:47], v[46:47], v[54:55] op_sel_hi:[1,0]
	v_pk_mul_f32 v[44:45], v[44:45], v[54:55] op_sel_hi:[1,0]
	v_pk_mul_f32 v[42:43], v[42:43], v[54:55] op_sel_hi:[1,0]
	v_pk_mul_f32 v[40:41], v[40:41], v[54:55] op_sel_hi:[1,0]
	v_pk_mul_f32 v[38:39], v[38:39], v[54:55] op_sel_hi:[1,0]
	v_pk_mul_f32 v[56:57], v[36:37], v[54:55] op_sel_hi:[1,0]
	v_pk_mul_f32 v[54:55], v[34:35], v[54:55] op_sel_hi:[1,0]
	v_cvt_pk_bf16_f32 v34, v46, v47
	v_cvt_pk_bf16_f32 v35, v48, v49
	v_cvt_pk_bf16_f32 v36, v42, v43
	v_cvt_pk_bf16_f32 v37, v44, v45
	global_store_dwordx4 v[52:53], v[34:37], off
	s_nop 1
	v_cvt_pk_bf16_f32 v34, v38, v39
	v_cvt_pk_bf16_f32 v35, v40, v41
	v_cvt_pk_bf16_f32 v36, v54, v55
	v_cvt_pk_bf16_f32 v37, v56, v57
	global_store_dwordx4 v[50:51], v[34:37], off offset:256
	s_nop 1
	v_mov_b32_e32 v38, v227
	v_mul_f32_e32 v38, 0x3e0293ee, v38
	v_add_co_u32_e32 v36, vcc, s66, v146
	v_lshl_add_u64 v[34:35], v[146:147], 0, s[26:27]
	s_nop 0
	v_addc_co_u32_e32 v37, vcc, 0, v147, vcc
	v_pk_mul_f32 v[32:33], v[32:33], v[38:39] op_sel_hi:[1,0]
	v_pk_mul_f32 v[30:31], v[30:31], v[38:39] op_sel_hi:[1,0]
	v_pk_mul_f32 v[28:29], v[28:29], v[38:39] op_sel_hi:[1,0]
	v_pk_mul_f32 v[26:27], v[26:27], v[38:39] op_sel_hi:[1,0]
	v_pk_mul_f32 v[24:25], v[24:25], v[38:39] op_sel_hi:[1,0]
	v_pk_mul_f32 v[22:23], v[22:23], v[38:39] op_sel_hi:[1,0]
	v_pk_mul_f32 v[40:41], v[20:21], v[38:39] op_sel_hi:[1,0]
	v_pk_mul_f32 v[38:39], v[18:19], v[38:39] op_sel_hi:[1,0]
	v_cvt_pk_bf16_f32 v18, v30, v31
	v_cvt_pk_bf16_f32 v19, v32, v33
	v_cvt_pk_bf16_f32 v20, v26, v27
	v_cvt_pk_bf16_f32 v21, v28, v29
	global_store_dwordx4 v[36:37], v[18:21], off
	s_andn2_b64 vcc, exec, s[4:5]
	s_nop 0
	v_cvt_pk_bf16_f32 v18, v22, v23
	v_cvt_pk_bf16_f32 v19, v24, v25
	v_cvt_pk_bf16_f32 v20, v38, v39
	v_cvt_pk_bf16_f32 v21, v40, v41
	global_store_dwordx4 v[34:35], v[18:21], off offset:256
	s_nop 1
	v_mov_b32_e32 v22, v228
	v_mul_f32_e32 v22, 0x3e0293ee, v22
	v_add_co_u32_e64 v20, s[4:5], s67, v146
	v_lshl_add_u64 v[18:19], v[146:147], 0, s[28:29]
	s_nop 0
	v_addc_co_u32_e64 v21, s[4:5], 0, v147, s[4:5]
	v_pk_mul_f32 v[16:17], v[16:17], v[22:23] op_sel_hi:[1,0]
	v_pk_mul_f32 v[14:15], v[14:15], v[22:23] op_sel_hi:[1,0]
	v_pk_mul_f32 v[12:13], v[12:13], v[22:23] op_sel_hi:[1,0]
	v_pk_mul_f32 v[10:11], v[10:11], v[22:23] op_sel_hi:[1,0]
	v_pk_mul_f32 v[8:9], v[8:9], v[22:23] op_sel_hi:[1,0]
	v_pk_mul_f32 v[6:7], v[6:7], v[22:23] op_sel_hi:[1,0]
	v_pk_mul_f32 v[24:25], v[4:5], v[22:23] op_sel_hi:[1,0]
	v_pk_mul_f32 v[22:23], v[2:3], v[22:23] op_sel_hi:[1,0]
	v_cvt_pk_bf16_f32 v2, v14, v15
	v_cvt_pk_bf16_f32 v3, v16, v17
	v_cvt_pk_bf16_f32 v4, v10, v11
	v_cvt_pk_bf16_f32 v5, v12, v13
	s_mov_b64 s[4:5], -1
	global_store_dwordx4 v[20:21], v[2:5], off
	s_nop 1
	v_cvt_pk_bf16_f32 v2, v6, v7
	v_cvt_pk_bf16_f32 v3, v8, v9
	v_cvt_pk_bf16_f32 v4, v22, v23
	v_cvt_pk_bf16_f32 v5, v24, v25
	global_store_dwordx4 v[18:19], v[2:5], off offset:256
	s_cbranch_vccnz .LBB0_1521
	s_andn2_b64 vcc, exec, s[6:7]
	s_cbranch_vccnz .LBB0_1520
	s_barrier
	s_branch .LBB0_1520

.LBB0_1843:
	v_mov_b32_e32 v155, v150
	v_mov_b32_e32 v146, v1
	s_lshl_b32 s17, s24, 8
	s_add_i32 s17, s17, s40
	v_add_u32_e32 v146, s17, v146
	v_ashrrev_i32_e32 v147, 31, v146
	v_lshl_add_u64 v[148:149], v[146:147], 2, s[10:11]
	global_load_dword v156, v[148:149], off
	global_load_dword v222, v[148:149], off offset:64
	global_load_dword v223, v[148:149], off offset:128
	global_load_dword v224, v[148:149], off offset:192
	global_load_dword v225, v[148:149], off offset:512
	global_load_dword v226, v[148:149], off offset:576
	global_load_dword v227, v[148:149], off offset:640
	global_load_dword v228, v[148:149], off offset:704
	v_mov_b32_e32 v161, v120
	v_mov_b32_e32 v120, v117
	s_lshl_b32 s17, s49, 7
	v_mov_b32_e32 v158, v126
	v_mov_b32_e32 v159, v122
	v_mov_b32_e32 v122, v127
	v_mov_b32_e32 v126, v128
	v_mov_b32_e32 v127, v124
	v_mov_b32_e32 v124, v129
	v_mov_b32_e32 v128, v114
	v_mov_b32_e32 v129, v118
	v_mov_b32_e32 v118, v115
	v_mov_b32_e32 v160, v116
	s_or_b32 s17, s17, s41
	v_lshl_add_u32 v116, v155, 3, s17
	v_mov_b64_e32 v[114:115], s[8:9]
	v_ashrrev_i32_e32 v117, 31, v116
	v_mad_i64_i32 v[162:163], s[26:27], v146, s48, v[114:115]
	v_lshlrev_b64 v[116:117], 1, v[116:117]
	v_lshl_add_u64 v[162:163], v[162:163], 0, v[116:117]
	s_andn2_b64 vcc, exec, s[4:5]
	s_waitcnt vmcnt(0)
	v_pk_mul_f32 v[120:121], v[120:121], v[156:157] op_sel_hi:[1,0]
	v_pk_mul_f32 v[158:159], v[158:159], v[156:157] op_sel_hi:[1,0]
	v_pk_mul_f32 v[122:123], v[122:123], v[156:157] op_sel_hi:[1,0]
	v_pk_mul_f32 v[126:127], v[126:127], v[156:157] op_sel_hi:[1,0]
	v_pk_mul_f32 v[124:125], v[124:125], v[156:157] op_sel_hi:[1,0]
	v_pk_mul_f32 v[128:129], v[128:129], v[156:157] op_sel_hi:[1,0]
	v_pk_mul_f32 v[118:119], v[118:119], v[156:157] op_sel_hi:[1,0]
	v_pk_mul_f32 v[160:161], v[160:161], v[156:157] op_sel_hi:[1,0]
	v_mul_f32_e32 v167, 0xbfb8aa3b, v121
	v_mul_f32_e32 v147, 0xbfb8aa3b, v159
	v_mul_f32_e32 v155, 0xbfb8aa3b, v123
	v_mul_f32_e32 v156, 0xbfb8aa3b, v127
	v_mul_f32_e32 v157, 0xbfb8aa3b, v125
	v_mul_f32_e32 v164, 0xbfb8aa3b, v129
	v_mul_f32_e32 v165, 0xbfb8aa3b, v119
	v_mul_f32_e32 v166, 0xbfb8aa3b, v161
	v_exp_f32_e32 v167, v167
	v_exp_f32_e32 v147, v147
	v_exp_f32_e32 v155, v155
	v_exp_f32_e32 v156, v156
	v_exp_f32_e32 v157, v157
	v_exp_f32_e32 v164, v164
	v_exp_f32_e32 v165, v165
	v_exp_f32_e32 v166, v166
	v_add_f32_e32 v167, 1.0, v167
	v_add_f32_e32 v147, 1.0, v147
	v_add_f32_e32 v155, 1.0, v155
	v_add_f32_e32 v156, 1.0, v156
	v_add_f32_e32 v157, 1.0, v157
	v_add_f32_e32 v164, 1.0, v164
	v_add_f32_e32 v165, 1.0, v165
	v_add_f32_e32 v166, 1.0, v166
	v_rcp_f32_e32 v167, v167
	v_rcp_f32_e32 v147, v147
	v_rcp_f32_e32 v155, v155
	v_rcp_f32_e32 v156, v156
	v_rcp_f32_e32 v157, v157
	v_rcp_f32_e32 v164, v164
	v_rcp_f32_e32 v165, v165
	v_rcp_f32_e32 v166, v166
	v_mul_f32_e32 v121, v121, v167
	v_mul_f32_e32 v147, v159, v147
	v_mul_f32_e32 v123, v123, v155
	v_mul_f32_e32 v127, v127, v156
	v_mul_f32_e32 v125, v125, v157
	v_mul_f32_e32 v129, v129, v164
	v_mul_f32_e32 v119, v119, v165
	v_mul_f32_e32 v155, v161, v166
	v_mul_f32_e32 v121, v120, v121
	v_mul_f32_e32 v147, v158, v147
	v_mul_f32_e32 v122, v122, v123
	v_mul_f32_e32 v123, v126, v127
	v_mul_f32_e32 v124, v124, v125
	v_mul_f32_e32 v125, v128, v129
	v_mul_f32_e32 v126, v118, v119
	v_mul_f32_e32 v127, v160, v155
	v_cvt_pk_bf16_f32 v118, v147, v122
	v_cvt_pk_bf16_f32 v119, v123, v124
	v_cvt_pk_bf16_f32 v120, v125, v126
	v_cvt_pk_bf16_f32 v121, v127, v121
	global_store_dwordx4 v[162:163], v[118:121], off
	s_nop 1
	v_mov_b32_e32 v118, v222
	s_nop 0
	v_mov_b32_e32 v120, v110
	v_mov_b32_e32 v110, v112
	v_mov_b32_e32 v112, v98
	v_mov_b32_e32 v98, v100
	v_add_u32_e32 v100, 16, v146
	v_mov_b32_e32 v121, v106
	v_mov_b32_e32 v106, v111
	v_mov_b32_e32 v111, v108
	v_mov_b32_e32 v108, v113
	v_mov_b32_e32 v113, v102
	v_mov_b32_e32 v102, v99
	v_mov_b32_e32 v99, v104
	v_mov_b32_e32 v104, v101
	v_mad_i64_i32 v[100:101], s[26:27], v100, s48, v[114:115]
	v_lshl_add_u64 v[122:123], v[100:101], 0, v[116:117]
	v_pk_mul_f32 v[100:101], v[120:121], v[118:119] op_sel_hi:[1,0]
	v_pk_mul_f32 v[106:107], v[106:107], v[118:119] op_sel_hi:[1,0]
	v_pk_mul_f32 v[110:111], v[110:111], v[118:119] op_sel_hi:[1,0]
	v_pk_mul_f32 v[108:109], v[108:109], v[118:119] op_sel_hi:[1,0]
	v_pk_mul_f32 v[112:113], v[112:113], v[118:119] op_sel_hi:[1,0]
	v_pk_mul_f32 v[102:103], v[102:103], v[118:119] op_sel_hi:[1,0]
	v_pk_mul_f32 v[98:99], v[98:99], v[118:119] op_sel_hi:[1,0]
	v_pk_mul_f32 v[104:105], v[104:105], v[118:119] op_sel_hi:[1,0]
	v_mul_f32_e32 v118, 0xbfb8aa3b, v101
	v_mul_f32_e32 v119, 0xbfb8aa3b, v107
	v_mul_f32_e32 v120, 0xbfb8aa3b, v111
	v_mul_f32_e32 v121, 0xbfb8aa3b, v109
	v_mul_f32_e32 v124, 0xbfb8aa3b, v113
	v_mul_f32_e32 v125, 0xbfb8aa3b, v103
	v_mul_f32_e32 v126, 0xbfb8aa3b, v99
	v_mul_f32_e32 v127, 0xbfb8aa3b, v105
	v_exp_f32_e32 v118, v118
	v_exp_f32_e32 v119, v119
	v_exp_f32_e32 v120, v120
	v_exp_f32_e32 v121, v121
	v_exp_f32_e32 v124, v124
	v_exp_f32_e32 v125, v125
	v_exp_f32_e32 v126, v126
	v_exp_f32_e32 v127, v127
	v_add_f32_e32 v118, 1.0, v118
	v_add_f32_e32 v119, 1.0, v119
	v_add_f32_e32 v120, 1.0, v120
	v_add_f32_e32 v121, 1.0, v121
	v_add_f32_e32 v124, 1.0, v124
	v_add_f32_e32 v125, 1.0, v125
	v_add_f32_e32 v126, 1.0, v126
	v_add_f32_e32 v127, 1.0, v127
	v_rcp_f32_e32 v118, v118
	v_rcp_f32_e32 v119, v119
	v_rcp_f32_e32 v120, v120
	v_rcp_f32_e32 v121, v121
	v_rcp_f32_e32 v124, v124
	v_rcp_f32_e32 v125, v125
	v_rcp_f32_e32 v126, v126
	v_rcp_f32_e32 v127, v127
	v_mul_f32_e32 v101, v101, v118
	v_mul_f32_e32 v107, v107, v119
	v_mul_f32_e32 v111, v111, v120
	v_mul_f32_e32 v109, v109, v121
	v_mul_f32_e32 v113, v113, v124
	v_mul_f32_e32 v103, v103, v125
	v_mul_f32_e32 v99, v99, v126
	v_mul_f32_e32 v105, v105, v127
	v_mul_f32_e32 v100, v100, v101
	v_mul_f32_e32 v101, v106, v107
	v_mul_f32_e32 v106, v110, v111
	v_mul_f32_e32 v107, v108, v109
	v_mul_f32_e32 v108, v112, v113
	v_mul_f32_e32 v102, v102, v103
	v_mul_f32_e32 v103, v98, v99
	v_mul_f32_e32 v104, v104, v105
	v_cvt_pk_bf16_f32 v98, v100, v101
	v_cvt_pk_bf16_f32 v99, v106, v107
	v_cvt_pk_bf16_f32 v100, v108, v102
	v_cvt_pk_bf16_f32 v101, v103, v104
	global_store_dwordx4 v[122:123], v[98:101], off
	s_nop 1
	v_mov_b32_e32 v98, v223
	s_nop 0
	v_mov_b32_e32 v100, v94
	v_mov_b32_e32 v94, v96
	v_mov_b32_e32 v96, v82
	v_mov_b32_e32 v82, v84
	v_add_u32_e32 v84, 32, v146
	v_mov_b32_e32 v101, v90
	v_mov_b32_e32 v90, v95
	v_mov_b32_e32 v95, v92
	v_mov_b32_e32 v92, v97
	v_mov_b32_e32 v97, v86
	v_mov_b32_e32 v86, v83
	v_mov_b32_e32 v83, v88
	v_mov_b32_e32 v88, v85
	v_mad_i64_i32 v[84:85], s[26:27], v84, s48, v[114:115]
	v_lshl_add_u64 v[102:103], v[84:85], 0, v[116:117]
	v_pk_mul_f32 v[84:85], v[100:101], v[98:99] op_sel_hi:[1,0]
	v_pk_mul_f32 v[90:91], v[90:91], v[98:99] op_sel_hi:[1,0]
	v_pk_mul_f32 v[94:95], v[94:95], v[98:99] op_sel_hi:[1,0]
	v_pk_mul_f32 v[92:93], v[92:93], v[98:99] op_sel_hi:[1,0]
	v_pk_mul_f32 v[96:97], v[96:97], v[98:99] op_sel_hi:[1,0]
	v_pk_mul_f32 v[86:87], v[86:87], v[98:99] op_sel_hi:[1,0]
	v_pk_mul_f32 v[82:83], v[82:83], v[98:99] op_sel_hi:[1,0]
	v_pk_mul_f32 v[88:89], v[88:89], v[98:99] op_sel_hi:[1,0]
	v_mul_f32_e32 v98, 0xbfb8aa3b, v85
	v_mul_f32_e32 v99, 0xbfb8aa3b, v91
	v_mul_f32_e32 v100, 0xbfb8aa3b, v95
	v_mul_f32_e32 v101, 0xbfb8aa3b, v93
	v_mul_f32_e32 v104, 0xbfb8aa3b, v97
	v_mul_f32_e32 v105, 0xbfb8aa3b, v87
	v_mul_f32_e32 v106, 0xbfb8aa3b, v83
	v_mul_f32_e32 v107, 0xbfb8aa3b, v89
	v_exp_f32_e32 v98, v98
	v_exp_f32_e32 v99, v99
	v_exp_f32_e32 v100, v100
	v_exp_f32_e32 v101, v101
	v_exp_f32_e32 v104, v104
	v_exp_f32_e32 v105, v105
	v_exp_f32_e32 v106, v106
	v_exp_f32_e32 v107, v107
	v_add_f32_e32 v98, 1.0, v98
	v_add_f32_e32 v99, 1.0, v99
	v_add_f32_e32 v100, 1.0, v100
	v_add_f32_e32 v101, 1.0, v101
	v_add_f32_e32 v104, 1.0, v104
	v_add_f32_e32 v105, 1.0, v105
	v_add_f32_e32 v106, 1.0, v106
	v_add_f32_e32 v107, 1.0, v107
	v_rcp_f32_e32 v98, v98
	v_rcp_f32_e32 v99, v99
	v_rcp_f32_e32 v100, v100
	v_rcp_f32_e32 v101, v101
	v_rcp_f32_e32 v104, v104
	v_rcp_f32_e32 v105, v105
	v_rcp_f32_e32 v106, v106
	v_rcp_f32_e32 v107, v107
	v_mul_f32_e32 v85, v85, v98
	v_mul_f32_e32 v91, v91, v99
	v_mul_f32_e32 v95, v95, v100
	v_mul_f32_e32 v93, v93, v101
	v_mul_f32_e32 v97, v97, v104
	v_mul_f32_e32 v87, v87, v105
	v_mul_f32_e32 v83, v83, v106
	v_mul_f32_e32 v89, v89, v107
	v_mul_f32_e32 v84, v84, v85
	v_mul_f32_e32 v85, v90, v91
	v_mul_f32_e32 v90, v94, v95
	v_mul_f32_e32 v91, v92, v93
	v_mul_f32_e32 v92, v96, v97
	v_mul_f32_e32 v86, v86, v87
	v_mul_f32_e32 v87, v82, v83
	v_mul_f32_e32 v88, v88, v89
	v_cvt_pk_bf16_f32 v82, v84, v85
	v_cvt_pk_bf16_f32 v83, v90, v91
	v_cvt_pk_bf16_f32 v84, v92, v86
	v_cvt_pk_bf16_f32 v85, v87, v88
	global_store_dwordx4 v[102:103], v[82:85], off
	s_nop 1
	v_mov_b32_e32 v82, v224
	s_nop 0
	v_mov_b32_e32 v84, v78
	v_mov_b32_e32 v78, v80
	v_mov_b32_e32 v80, v66
	v_mov_b32_e32 v66, v68
	v_add_u32_e32 v68, 48, v146
	v_mov_b32_e32 v85, v74
	v_mov_b32_e32 v74, v79
	v_mov_b32_e32 v79, v76
	v_mov_b32_e32 v76, v81
	v_mov_b32_e32 v81, v70
	v_mov_b32_e32 v70, v67
	v_mov_b32_e32 v67, v72
	v_mov_b32_e32 v72, v69
	v_mad_i64_i32 v[68:69], s[26:27], v68, s48, v[114:115]
	v_lshl_add_u64 v[86:87], v[68:69], 0, v[116:117]
	v_pk_mul_f32 v[68:69], v[84:85], v[82:83] op_sel_hi:[1,0]
	v_pk_mul_f32 v[74:75], v[74:75], v[82:83] op_sel_hi:[1,0]
	v_pk_mul_f32 v[78:79], v[78:79], v[82:83] op_sel_hi:[1,0]
	v_pk_mul_f32 v[76:77], v[76:77], v[82:83] op_sel_hi:[1,0]
	v_pk_mul_f32 v[80:81], v[80:81], v[82:83] op_sel_hi:[1,0]
	v_pk_mul_f32 v[70:71], v[70:71], v[82:83] op_sel_hi:[1,0]
	v_pk_mul_f32 v[66:67], v[66:67], v[82:83] op_sel_hi:[1,0]
	v_pk_mul_f32 v[72:73], v[72:73], v[82:83] op_sel_hi:[1,0]
	v_mul_f32_e32 v82, 0xbfb8aa3b, v69
	v_mul_f32_e32 v83, 0xbfb8aa3b, v75
	v_mul_f32_e32 v84, 0xbfb8aa3b, v79
	v_mul_f32_e32 v85, 0xbfb8aa3b, v77
	v_mul_f32_e32 v88, 0xbfb8aa3b, v81
	v_mul_f32_e32 v89, 0xbfb8aa3b, v71
	v_mul_f32_e32 v90, 0xbfb8aa3b, v67
	v_mul_f32_e32 v91, 0xbfb8aa3b, v73
	v_exp_f32_e32 v82, v82
	v_exp_f32_e32 v83, v83
	v_exp_f32_e32 v84, v84
	v_exp_f32_e32 v85, v85
	v_exp_f32_e32 v88, v88
	v_exp_f32_e32 v89, v89
	v_exp_f32_e32 v90, v90
	v_exp_f32_e32 v91, v91
	v_add_f32_e32 v82, 1.0, v82
	v_add_f32_e32 v83, 1.0, v83
	v_add_f32_e32 v84, 1.0, v84
	v_add_f32_e32 v85, 1.0, v85
	v_add_f32_e32 v88, 1.0, v88
	v_add_f32_e32 v89, 1.0, v89
	v_add_f32_e32 v90, 1.0, v90
	v_add_f32_e32 v91, 1.0, v91
	v_rcp_f32_e32 v82, v82
	v_rcp_f32_e32 v83, v83
	v_rcp_f32_e32 v84, v84
	v_rcp_f32_e32 v85, v85
	v_rcp_f32_e32 v88, v88
	v_rcp_f32_e32 v89, v89
	v_rcp_f32_e32 v90, v90
	v_rcp_f32_e32 v91, v91
	v_mul_f32_e32 v69, v69, v82
	v_mul_f32_e32 v75, v75, v83
	v_mul_f32_e32 v79, v79, v84
	v_mul_f32_e32 v77, v77, v85
	v_mul_f32_e32 v81, v81, v88
	v_mul_f32_e32 v71, v71, v89
	v_mul_f32_e32 v67, v67, v90
	v_mul_f32_e32 v73, v73, v91
	v_mul_f32_e32 v68, v68, v69
	v_mul_f32_e32 v69, v74, v75
	v_mul_f32_e32 v74, v78, v79
	v_mul_f32_e32 v75, v76, v77
	v_mul_f32_e32 v76, v80, v81
	v_mul_f32_e32 v70, v70, v71
	v_mul_f32_e32 v71, v66, v67
	v_mul_f32_e32 v72, v72, v73
	v_cvt_pk_bf16_f32 v66, v68, v69
	v_cvt_pk_bf16_f32 v67, v74, v75
	v_cvt_pk_bf16_f32 v68, v76, v70
	v_cvt_pk_bf16_f32 v69, v71, v72
	global_store_dwordx4 v[86:87], v[66:69], off
	s_nop 1
	v_mov_b32_e32 v66, v225
	s_nop 0
	v_mov_b32_e32 v68, v62
	v_mov_b32_e32 v62, v64
	v_mov_b32_e32 v64, v50
	v_mov_b32_e32 v50, v52
	v_add_u32_e32 v52, 0x80, v146
	v_mov_b32_e32 v69, v58
	v_mov_b32_e32 v58, v63
	v_mov_b32_e32 v63, v60
	v_mov_b32_e32 v60, v65
	v_mov_b32_e32 v65, v54
	v_mov_b32_e32 v54, v51
	v_mov_b32_e32 v51, v56
	v_mov_b32_e32 v56, v53
	v_mad_i64_i32 v[52:53], s[26:27], v52, s48, v[114:115]
	v_lshl_add_u64 v[70:71], v[52:53], 0, v[116:117]
	v_pk_mul_f32 v[52:53], v[68:69], v[66:67] op_sel_hi:[1,0]
	v_pk_mul_f32 v[58:59], v[58:59], v[66:67] op_sel_hi:[1,0]
	v_pk_mul_f32 v[62:63], v[62:63], v[66:67] op_sel_hi:[1,0]
	v_pk_mul_f32 v[60:61], v[60:61], v[66:67] op_sel_hi:[1,0]
	v_pk_mul_f32 v[64:65], v[64:65], v[66:67] op_sel_hi:[1,0]
	v_pk_mul_f32 v[54:55], v[54:55], v[66:67] op_sel_hi:[1,0]
	v_pk_mul_f32 v[50:51], v[50:51], v[66:67] op_sel_hi:[1,0]
	v_pk_mul_f32 v[56:57], v[56:57], v[66:67] op_sel_hi:[1,0]
	v_mul_f32_e32 v66, 0xbfb8aa3b, v53
	v_mul_f32_e32 v67, 0xbfb8aa3b, v59
	v_mul_f32_e32 v68, 0xbfb8aa3b, v63
	v_mul_f32_e32 v69, 0xbfb8aa3b, v61
	v_mul_f32_e32 v72, 0xbfb8aa3b, v65
	v_mul_f32_e32 v73, 0xbfb8aa3b, v55
	v_mul_f32_e32 v74, 0xbfb8aa3b, v51
	v_mul_f32_e32 v75, 0xbfb8aa3b, v57
	v_exp_f32_e32 v66, v66
	v_exp_f32_e32 v67, v67
	v_exp_f32_e32 v68, v68
	v_exp_f32_e32 v69, v69
	v_exp_f32_e32 v72, v72
	v_exp_f32_e32 v73, v73
	v_exp_f32_e32 v74, v74
	v_exp_f32_e32 v75, v75
	v_add_f32_e32 v66, 1.0, v66
	v_add_f32_e32 v67, 1.0, v67
	v_add_f32_e32 v68, 1.0, v68
	v_add_f32_e32 v69, 1.0, v69
	v_add_f32_e32 v72, 1.0, v72
	v_add_f32_e32 v73, 1.0, v73
	v_add_f32_e32 v74, 1.0, v74
	v_add_f32_e32 v75, 1.0, v75
	v_rcp_f32_e32 v66, v66
	v_rcp_f32_e32 v67, v67
	v_rcp_f32_e32 v68, v68
	v_rcp_f32_e32 v69, v69
	v_rcp_f32_e32 v72, v72
	v_rcp_f32_e32 v73, v73
	v_rcp_f32_e32 v74, v74
	v_rcp_f32_e32 v75, v75
	v_mul_f32_e32 v53, v53, v66
	v_mul_f32_e32 v59, v59, v67
	v_mul_f32_e32 v63, v63, v68
	v_mul_f32_e32 v61, v61, v69
	v_mul_f32_e32 v65, v65, v72
	v_mul_f32_e32 v55, v55, v73
	v_mul_f32_e32 v51, v51, v74
	v_mul_f32_e32 v57, v57, v75
	v_mul_f32_e32 v52, v52, v53
	v_mul_f32_e32 v53, v58, v59
	v_mul_f32_e32 v58, v62, v63
	v_mul_f32_e32 v59, v60, v61
	v_mul_f32_e32 v60, v64, v65
	v_mul_f32_e32 v54, v54, v55
	v_mul_f32_e32 v55, v50, v51
	v_mul_f32_e32 v56, v56, v57
	v_cvt_pk_bf16_f32 v50, v52, v53
	v_cvt_pk_bf16_f32 v51, v58, v59
	v_cvt_pk_bf16_f32 v52, v60, v54
	v_cvt_pk_bf16_f32 v53, v55, v56
	global_store_dwordx4 v[70:71], v[50:53], off
	s_nop 1
	v_mov_b32_e32 v50, v226
	s_nop 0
	v_mov_b32_e32 v52, v46
	v_mov_b32_e32 v46, v48
	v_mov_b32_e32 v48, v34
	v_mov_b32_e32 v34, v36
	v_add_u32_e32 v36, 0x90, v146
	v_mov_b32_e32 v53, v42
	v_mov_b32_e32 v42, v47
	v_mov_b32_e32 v47, v44
	v_mov_b32_e32 v44, v49
	v_mov_b32_e32 v49, v38
	v_mov_b32_e32 v38, v35
	v_mov_b32_e32 v35, v40
	v_mov_b32_e32 v40, v37
	v_mad_i64_i32 v[36:37], s[26:27], v36, s48, v[114:115]
	v_lshl_add_u64 v[54:55], v[36:37], 0, v[116:117]
	v_pk_mul_f32 v[36:37], v[52:53], v[50:51] op_sel_hi:[1,0]
	v_pk_mul_f32 v[42:43], v[42:43], v[50:51] op_sel_hi:[1,0]
	v_pk_mul_f32 v[46:47], v[46:47], v[50:51] op_sel_hi:[1,0]
	v_pk_mul_f32 v[44:45], v[44:45], v[50:51] op_sel_hi:[1,0]
	v_pk_mul_f32 v[48:49], v[48:49], v[50:51] op_sel_hi:[1,0]
	v_pk_mul_f32 v[38:39], v[38:39], v[50:51] op_sel_hi:[1,0]
	v_pk_mul_f32 v[34:35], v[34:35], v[50:51] op_sel_hi:[1,0]
	v_pk_mul_f32 v[40:41], v[40:41], v[50:51] op_sel_hi:[1,0]
	v_mul_f32_e32 v50, 0xbfb8aa3b, v37
	v_mul_f32_e32 v51, 0xbfb8aa3b, v43
	v_mul_f32_e32 v52, 0xbfb8aa3b, v47
	v_mul_f32_e32 v53, 0xbfb8aa3b, v45
	v_mul_f32_e32 v56, 0xbfb8aa3b, v49
	v_mul_f32_e32 v57, 0xbfb8aa3b, v39
	v_mul_f32_e32 v58, 0xbfb8aa3b, v35
	v_mul_f32_e32 v59, 0xbfb8aa3b, v41
	v_exp_f32_e32 v50, v50
	v_exp_f32_e32 v51, v51
	v_exp_f32_e32 v52, v52
	v_exp_f32_e32 v53, v53
	v_exp_f32_e32 v56, v56
	v_exp_f32_e32 v57, v57
	v_exp_f32_e32 v58, v58
	v_exp_f32_e32 v59, v59
	v_add_f32_e32 v50, 1.0, v50
	v_add_f32_e32 v51, 1.0, v51
	v_add_f32_e32 v52, 1.0, v52
	v_add_f32_e32 v53, 1.0, v53
	v_add_f32_e32 v56, 1.0, v56
	v_add_f32_e32 v57, 1.0, v57
	v_add_f32_e32 v58, 1.0, v58
	v_add_f32_e32 v59, 1.0, v59
	v_rcp_f32_e32 v50, v50
	v_rcp_f32_e32 v51, v51
	v_rcp_f32_e32 v52, v52
	v_rcp_f32_e32 v53, v53
	v_rcp_f32_e32 v56, v56
	v_rcp_f32_e32 v57, v57
	v_rcp_f32_e32 v58, v58
	v_rcp_f32_e32 v59, v59
	v_mul_f32_e32 v37, v37, v50
	v_mul_f32_e32 v43, v43, v51
	v_mul_f32_e32 v47, v47, v52
	v_mul_f32_e32 v45, v45, v53
	v_mul_f32_e32 v49, v49, v56
	v_mul_f32_e32 v39, v39, v57
	v_mul_f32_e32 v35, v35, v58
	v_mul_f32_e32 v41, v41, v59
	v_mul_f32_e32 v36, v36, v37
	v_mul_f32_e32 v37, v42, v43
	v_mul_f32_e32 v42, v46, v47
	v_mul_f32_e32 v43, v44, v45
	v_mul_f32_e32 v44, v48, v49
	v_mul_f32_e32 v38, v38, v39
	v_mul_f32_e32 v39, v34, v35
	v_mul_f32_e32 v40, v40, v41
	v_cvt_pk_bf16_f32 v34, v36, v37
	v_cvt_pk_bf16_f32 v35, v42, v43
	v_cvt_pk_bf16_f32 v36, v44, v38
	v_cvt_pk_bf16_f32 v37, v39, v40
	global_store_dwordx4 v[54:55], v[34:37], off
	s_nop 1
	v_mov_b32_e32 v34, v227
	s_nop 0
	v_mov_b32_e32 v36, v30
	v_mov_b32_e32 v30, v32
	v_mov_b32_e32 v32, v18
	v_mov_b32_e32 v18, v20
	v_add_u32_e32 v20, 0xa0, v146
	v_mov_b32_e32 v37, v26
	v_mov_b32_e32 v26, v31
	v_mov_b32_e32 v31, v28
	v_mov_b32_e32 v28, v33
	v_mov_b32_e32 v33, v22
	v_mov_b32_e32 v22, v19
	v_mov_b32_e32 v19, v24
	v_mov_b32_e32 v24, v21
	v_mad_i64_i32 v[20:21], s[26:27], v20, s48, v[114:115]
	v_lshl_add_u64 v[38:39], v[20:21], 0, v[116:117]
	v_pk_mul_f32 v[20:21], v[36:37], v[34:35] op_sel_hi:[1,0]
	v_pk_mul_f32 v[26:27], v[26:27], v[34:35] op_sel_hi:[1,0]
	v_pk_mul_f32 v[30:31], v[30:31], v[34:35] op_sel_hi:[1,0]
	v_pk_mul_f32 v[28:29], v[28:29], v[34:35] op_sel_hi:[1,0]
	v_pk_mul_f32 v[32:33], v[32:33], v[34:35] op_sel_hi:[1,0]
	v_pk_mul_f32 v[22:23], v[22:23], v[34:35] op_sel_hi:[1,0]
	v_pk_mul_f32 v[18:19], v[18:19], v[34:35] op_sel_hi:[1,0]
	v_pk_mul_f32 v[24:25], v[24:25], v[34:35] op_sel_hi:[1,0]
	v_mul_f32_e32 v34, 0xbfb8aa3b, v21
	v_mul_f32_e32 v35, 0xbfb8aa3b, v27
	v_mul_f32_e32 v36, 0xbfb8aa3b, v31
	v_mul_f32_e32 v37, 0xbfb8aa3b, v29
	v_mul_f32_e32 v40, 0xbfb8aa3b, v33
	v_mul_f32_e32 v41, 0xbfb8aa3b, v23
	v_mul_f32_e32 v42, 0xbfb8aa3b, v19
	v_mul_f32_e32 v43, 0xbfb8aa3b, v25
	v_exp_f32_e32 v34, v34
	v_exp_f32_e32 v35, v35
	v_exp_f32_e32 v36, v36
	v_exp_f32_e32 v37, v37
	v_exp_f32_e32 v40, v40
	v_exp_f32_e32 v41, v41
	v_exp_f32_e32 v42, v42
	v_exp_f32_e32 v43, v43
	v_add_f32_e32 v34, 1.0, v34
	v_add_f32_e32 v35, 1.0, v35
	v_add_f32_e32 v36, 1.0, v36
	v_add_f32_e32 v37, 1.0, v37
	v_add_f32_e32 v40, 1.0, v40
	v_add_f32_e32 v41, 1.0, v41
	v_add_f32_e32 v42, 1.0, v42
	v_add_f32_e32 v43, 1.0, v43
	v_rcp_f32_e32 v34, v34
	v_rcp_f32_e32 v35, v35
	v_rcp_f32_e32 v36, v36
	v_rcp_f32_e32 v37, v37
	v_rcp_f32_e32 v40, v40
	v_rcp_f32_e32 v41, v41
	v_rcp_f32_e32 v42, v42
	v_rcp_f32_e32 v43, v43
	v_mul_f32_e32 v21, v21, v34
	v_mul_f32_e32 v27, v27, v35
	v_mul_f32_e32 v31, v31, v36
	v_mul_f32_e32 v29, v29, v37
	v_mul_f32_e32 v33, v33, v40
	v_mul_f32_e32 v23, v23, v41
	v_mul_f32_e32 v19, v19, v42
	v_mul_f32_e32 v25, v25, v43
	v_mul_f32_e32 v20, v20, v21
	v_mul_f32_e32 v21, v26, v27
	v_mul_f32_e32 v26, v30, v31
	v_mul_f32_e32 v27, v28, v29
	v_mul_f32_e32 v28, v32, v33
	v_mul_f32_e32 v22, v22, v23
	v_mul_f32_e32 v23, v18, v19
	v_mul_f32_e32 v24, v24, v25
	v_cvt_pk_bf16_f32 v18, v20, v21
	v_cvt_pk_bf16_f32 v19, v26, v27
	v_cvt_pk_bf16_f32 v20, v28, v22
	v_cvt_pk_bf16_f32 v21, v23, v24
	global_store_dwordx4 v[38:39], v[18:21], off
	s_nop 1
	v_mov_b32_e32 v18, v228
	s_nop 0
	v_mov_b32_e32 v20, v14
	v_mov_b32_e32 v14, v16
	v_mov_b32_e32 v16, v2
	v_mov_b32_e32 v2, v4
	v_add_u32_e32 v4, 0xb0, v146
	v_mov_b32_e32 v21, v10
	v_mov_b32_e32 v10, v15
	v_mov_b32_e32 v15, v12
	v_mov_b32_e32 v12, v17
	v_mov_b32_e32 v17, v6
	v_mov_b32_e32 v6, v3
	v_mov_b32_e32 v3, v8
	v_mov_b32_e32 v8, v5
	v_mad_i64_i32 v[4:5], s[4:5], v4, s48, v[114:115]
	v_lshl_add_u64 v[22:23], v[4:5], 0, v[116:117]
	s_mov_b64 s[4:5], -1
	v_pk_mul_f32 v[4:5], v[20:21], v[18:19] op_sel_hi:[1,0]
	v_pk_mul_f32 v[10:11], v[10:11], v[18:19] op_sel_hi:[1,0]
	v_pk_mul_f32 v[14:15], v[14:15], v[18:19] op_sel_hi:[1,0]
	v_pk_mul_f32 v[12:13], v[12:13], v[18:19] op_sel_hi:[1,0]
	v_pk_mul_f32 v[16:17], v[16:17], v[18:19] op_sel_hi:[1,0]
	v_pk_mul_f32 v[6:7], v[6:7], v[18:19] op_sel_hi:[1,0]
	v_pk_mul_f32 v[2:3], v[2:3], v[18:19] op_sel_hi:[1,0]
	v_pk_mul_f32 v[8:9], v[8:9], v[18:19] op_sel_hi:[1,0]
	v_mul_f32_e32 v18, 0xbfb8aa3b, v5
	v_mul_f32_e32 v19, 0xbfb8aa3b, v11
	v_mul_f32_e32 v20, 0xbfb8aa3b, v15
	v_mul_f32_e32 v21, 0xbfb8aa3b, v13
	v_mul_f32_e32 v24, 0xbfb8aa3b, v17
	v_mul_f32_e32 v25, 0xbfb8aa3b, v7
	v_mul_f32_e32 v26, 0xbfb8aa3b, v3
	v_mul_f32_e32 v27, 0xbfb8aa3b, v9
	v_exp_f32_e32 v18, v18
	v_exp_f32_e32 v19, v19
	v_exp_f32_e32 v20, v20
	v_exp_f32_e32 v21, v21
	v_exp_f32_e32 v24, v24
	v_exp_f32_e32 v25, v25
	v_exp_f32_e32 v26, v26
	v_exp_f32_e32 v27, v27
	v_add_f32_e32 v18, 1.0, v18
	v_add_f32_e32 v19, 1.0, v19
	v_add_f32_e32 v20, 1.0, v20
	v_add_f32_e32 v21, 1.0, v21
	v_add_f32_e32 v24, 1.0, v24
	v_add_f32_e32 v25, 1.0, v25
	v_add_f32_e32 v26, 1.0, v26
	v_add_f32_e32 v27, 1.0, v27
	v_rcp_f32_e32 v18, v18
	v_rcp_f32_e32 v19, v19
	v_rcp_f32_e32 v20, v20
	v_rcp_f32_e32 v21, v21
	v_rcp_f32_e32 v24, v24
	v_rcp_f32_e32 v25, v25
	v_rcp_f32_e32 v26, v26
	v_rcp_f32_e32 v27, v27
	v_mul_f32_e32 v5, v5, v18
	v_mul_f32_e32 v11, v11, v19
	v_mul_f32_e32 v15, v15, v20
	v_mul_f32_e32 v13, v13, v21
	v_mul_f32_e32 v17, v17, v24
	v_mul_f32_e32 v7, v7, v25
	v_mul_f32_e32 v3, v3, v26
	v_mul_f32_e32 v9, v9, v27
	v_mul_f32_e32 v4, v4, v5
	v_mul_f32_e32 v5, v10, v11
	v_mul_f32_e32 v10, v14, v15
	v_mul_f32_e32 v11, v12, v13
	v_mul_f32_e32 v12, v16, v17
	v_mul_f32_e32 v6, v6, v7
	v_mul_f32_e32 v7, v2, v3
	v_mul_f32_e32 v8, v8, v9
	v_cvt_pk_bf16_f32 v2, v4, v5
	v_cvt_pk_bf16_f32 v3, v10, v11
	v_cvt_pk_bf16_f32 v4, v12, v6
	v_cvt_pk_bf16_f32 v5, v7, v8
	global_store_dwordx4 v[22:23], v[2:5], off
	s_cbranch_vccnz .LBB0_1836
	s_andn2_b64 vcc, exec, s[6:7]
	s_cbranch_vccnz .LBB0_1835
	s_barrier
	s_branch .LBB0_1835
